# removed one provably redundant ping-pong barrier in each of the 8 K-loop tails (after the vmcnt(0) publish and the lag barrier nothing writes the stage buffers)
# speedup vs baseline: 1.0037x; 1.0013x over previous
; #define LDA8(dst, b, h) _Pragma("unroll") for (int m = 0; m < 4; ++m) _Pragma("unroll") for (int k = 0; k < 2; ++k) \
;     dst[m][k] = *(const bf16x8*)((const char*)SA8(b, h) + lds_byte8(wr * 64 + m * 16 + fr, k * 32 + fq * 8))
; #define LDB8(dst, b, h) _Pragma("unroll") for (int n = 0; n < 2; ++n) _Pragma("unroll") for (int k = 0; k < 2; ++k) \
;     dst[n][k] = *(const bf16x8*)((const char*)SB8(b, h) + lds_byte8(wc * 32 + n * 16 + fr, k * 32 + fq * 8))
; #define WAIT_V8(n) asm volatile("s_waitcnt vmcnt(" #n ")" ::: "memory")
; #define WAIT_L8(n) asm volatile("s_waitcnt lgkmcnt(" #n ")" ::: "memory")
; #define BAR8 __builtin_amdgcn_s_barrier()
;     ...
;   { LDB8(B0, 0, 0); LDA8(At, 0, 0); STAGE8(SA8(1, 1), A, lda, brow + 128, nt - 1);
;     BAR8; WAIT_L8(0); MMA8(0, 0, At, B0); BAR8;
;     LDB8(B1, 0, 1); BAR8; WAIT_L8(0); MMA8(0, 1, At, B1); BAR8;
;     LDA8(At, 0, 1); WAIT_V8(4); BAR8; WAIT_L8(0); MMA8(1, 0, At, B0); MMA8(1, 1, At, B1); BAR8; }
.Lpk_exit_0:
	s_add_u32 s4, s4, 0x40780
	s_addc_u32 s5, s5, 0
	v_lshl_add_u64 v[132:133], s[4:5], 0, v[132:133]
	v_lshl_add_u64 v[0:1], v[0:1], 1, v[132:133]
	s_or_b32 m0, s100, 0xc000
	ds_read_b128 v[138:141], v173
	ds_read_b128 v[142:145], v173 offset:1024
	ds_read_b128 v[160:163], v173 offset:2048
	ds_read_b128 v[164:167], v173 offset:3072
	ds_read_b128 v[174:177], v156
	ds_read_b128 v[178:181], v156 offset:1024
	ds_read_b128 v[182:185], v154
	ds_read_b128 v[186:189], v154 offset:1024
	ds_read_b128 v[190:193], v153
	ds_read_b128 v[194:197], v153 offset:1024
	ds_read_b128 v[198:201], v152
	ds_read_b128 v[202:205], v152 offset:1024
	global_load_lds_dwordx4 v[0:1], off
	v_lshl_add_u64 v[0:1], s[4:5], 0, v[136:137]
	s_or_b32 m0, s100, 0xe000
	v_lshl_add_u64 v[0:1], v[134:135], 1, v[0:1]
	global_load_lds_dwordx4 v[0:1], off
	s_barrier
	s_waitcnt lgkmcnt(0)
	v_mfma_f32_16x16x32_f16 v[128:131], v[174:177], v[138:141], v[128:131]
	v_mfma_f32_16x16x32_f16 v[124:127], v[174:177], v[160:163], v[124:127]
	v_mfma_f32_16x16x32_f16 v[120:123], v[182:185], v[138:141], v[120:123]
	v_mfma_f32_16x16x32_f16 v[112:115], v[190:193], v[138:141], v[112:115]
	v_mfma_f32_16x16x32_f16 v[128:131], v[178:181], v[142:145], v[128:131]
	v_mfma_f32_16x16x32_f16 v[124:127], v[178:181], v[164:167], v[124:127]
	v_mfma_f32_16x16x32_f16 v[120:123], v[186:189], v[142:145], v[120:123]
	v_mfma_f32_16x16x32_f16 v[116:119], v[182:185], v[160:163], v[116:119]
	v_mfma_f32_16x16x32_f16 v[112:115], v[194:197], v[142:145], v[112:115]
	v_mfma_f32_16x16x32_f16 v[108:111], v[190:193], v[160:163], v[108:111]
	v_mfma_f32_16x16x32_f16 v[104:107], v[198:201], v[138:141], v[104:107]
	v_mfma_f32_16x16x32_f16 v[100:103], v[198:201], v[160:163], v[100:103]
	v_mfma_f32_16x16x32_f16 v[132:135], v[186:189], v[164:167], v[116:119]
	v_mfma_f32_16x16x32_f16 v[170:173], v[194:197], v[164:167], v[108:111]
	v_mfma_f32_16x16x32_f16 v[206:209], v[202:205], v[142:145], v[104:107]
	v_mfma_f32_16x16x32_f16 v[210:213], v[202:205], v[164:167], v[100:103]
	s_barrier
	s_nop 1
	ds_read_b128 v[100:103], v169
	ds_read_b128 v[104:107], v169 offset:1024
	ds_read_b128 v[108:111], v169 offset:2048
	ds_read_b128 v[116:119], v169 offset:3072
	s_barrier
	s_waitcnt lgkmcnt(0)
	v_mfma_f32_16x16x32_f16 v[80:83], v[190:193], v[100:103], v[80:83]
	v_mfma_f32_16x16x32_f16 v[76:79], v[190:193], v[108:111], v[76:79]
	v_mfma_f32_16x16x32_f16 v[72:75], v[198:201], v[100:103], v[72:75]
	v_mfma_f32_16x16x32_f16 v[68:71], v[198:201], v[108:111], v[68:71]
	v_mfma_f32_16x16x32_f16 v[96:99], v[174:177], v[100:103], v[96:99]
	v_mfma_f32_16x16x32_f16 v[92:95], v[174:177], v[108:111], v[92:95]
	v_mfma_f32_16x16x32_f16 v[88:91], v[182:185], v[100:103], v[88:91]
	v_mfma_f32_16x16x32_f16 v[84:87], v[182:185], v[108:111], v[84:87]
	v_mfma_f32_16x16x32_f16 v[80:83], v[194:197], v[104:107], v[80:83]
	v_mfma_f32_16x16x32_f16 v[76:79], v[194:197], v[116:119], v[76:79]
	v_mfma_f32_16x16x32_f16 v[72:75], v[202:205], v[104:107], v[72:75]
	v_mfma_f32_16x16x32_f16 v[68:71], v[202:205], v[116:119], v[68:71]
	v_mfma_f32_16x16x32_f16 v[214:217], v[178:181], v[104:107], v[96:99]
	v_mfma_f32_16x16x32_f16 v[174:177], v[178:181], v[116:119], v[92:95]
	v_mfma_f32_16x16x32_f16 v[178:181], v[186:189], v[104:107], v[88:91]
	v_mfma_f32_16x16x32_f16 v[182:185], v[186:189], v[116:119], v[84:87]
	s_barrier
	s_nop 0
	ds_read_b128 v[84:87], v156 offset:16384
	ds_read_b128 v[88:91], v156 offset:17408
	ds_read_b128 v[92:95], v154 offset:16384
	ds_read_b128 v[96:99], v154 offset:17408
	ds_read_b128 v[186:189], v153 offset:16384
	ds_read_b128 v[190:193], v153 offset:17408
	ds_read_b128 v[194:197], v152 offset:16384
	ds_read_b128 v[198:201], v152 offset:17408
	s_waitcnt vmcnt(4)
	s_barrier
	s_waitcnt lgkmcnt(0)
	v_mfma_f32_16x16x32_f16 v[64:67], v[84:87], v[138:141], v[64:67]
	v_mfma_f32_16x16x32_f16 v[60:63], v[84:87], v[160:163], v[60:63]
	v_mfma_f32_16x16x32_f16 v[56:59], v[92:95], v[138:141], v[56:59]
	v_mfma_f32_16x16x32_f16 v[52:55], v[92:95], v[160:163], v[52:55]
	v_mfma_f32_16x16x32_f16 v[48:51], v[186:189], v[138:141], v[48:51]
	v_mfma_f32_16x16x32_f16 v[44:47], v[186:189], v[160:163], v[44:47]
	v_mfma_f32_16x16x32_f16 v[64:67], v[88:91], v[142:145], v[64:67]
	v_mfma_f32_16x16x32_f16 v[60:63], v[88:91], v[164:167], v[60:63]
	v_mfma_f32_16x16x32_f16 v[56:59], v[96:99], v[142:145], v[56:59]
	v_mfma_f32_16x16x32_f16 v[52:55], v[96:99], v[164:167], v[52:55]
	v_mfma_f32_16x16x32_f16 v[48:51], v[190:193], v[142:145], v[48:51]
	v_mfma_f32_16x16x32_f16 v[44:47], v[190:193], v[164:167], v[44:47]
	v_mfma_f32_16x16x32_f16 v[40:43], v[194:197], v[138:141], v[40:43]
	v_mfma_f32_16x16x32_f16 v[36:39], v[194:197], v[160:163], v[36:39]
	v_mfma_f32_16x16x32_f16 v[136:139], v[198:201], v[142:145], v[40:43]
	v_mfma_f32_16x16x32_f16 v[140:143], v[198:201], v[164:167], v[36:39]
	v_mfma_f32_16x16x32_f16 v[32:35], v[84:87], v[100:103], v[32:35]
	v_mfma_f32_16x16x32_f16 v[28:31], v[84:87], v[108:111], v[28:31]
	v_mfma_f32_16x16x32_f16 v[24:27], v[92:95], v[100:103], v[24:27]
	v_mfma_f32_16x16x32_f16 v[20:23], v[92:95], v[108:111], v[20:23]
	v_mfma_f32_16x16x32_f16 v[16:19], v[186:189], v[100:103], v[16:19]
	v_mfma_f32_16x16x32_f16 v[12:15], v[186:189], v[108:111], v[12:15]
	v_mfma_f32_16x16x32_f16 v[8:11], v[194:197], v[100:103], v[8:11]
	v_mfma_f32_16x16x32_f16 v[4:7], v[194:197], v[108:111], v[4:7]
	v_mfma_f32_16x16x32_f16 v[160:163], v[88:91], v[104:107], v[32:35]
	v_mfma_f32_16x16x32_f16 v[164:167], v[88:91], v[116:119], v[28:31]
	v_mfma_f32_16x16x32_f16 v[202:205], v[96:99], v[104:107], v[24:27]
	v_mfma_f32_16x16x32_f16 v[218:221], v[96:99], v[116:119], v[20:23]
	v_mfma_f32_16x16x32_f16 v[230:233], v[190:193], v[104:107], v[16:19]
	v_mfma_f32_16x16x32_f16 v[186:189], v[190:193], v[116:119], v[12:15]
	v_mfma_f32_16x16x32_f16 v[190:193], v[198:201], v[104:107], v[8:11]
	v_mfma_f32_16x16x32_f16 v[194:197], v[198:201], v[116:119], v[4:7]
	s_barrier
; #define LDA8(dst, b, h) _Pragma("unroll") for (int m = 0; m < 4; ++m) _Pragma("unroll") for (int k = 0; k < 2; ++k) \
;     dst[m][k] = *(const bf16x8*)((const char*)SA8(b, h) + lds_byte8(wr * 64 + m * 16 + fr, k * 32 + fq * 8))
; #define LDB8(dst, b, h) _Pragma("unroll") for (int n = 0; n < 2; ++n) _Pragma("unroll") for (int k = 0; k < 2; ++k) \
;     dst[n][k] = *(const bf16x8*)((const char*)SB8(b, h) + lds_byte8(wc * 32 + n * 16 + fr, k * 32 + fq * 8))
; #define WAIT_V8(n) asm volatile("s_waitcnt vmcnt(" #n ")" ::: "memory")
; #define WAIT_L8(n) asm volatile("s_waitcnt lgkmcnt(" #n ")" ::: "memory")
; #define BAR8 __builtin_amdgcn_s_barrier()
;     ...
;   { LDB8(B0, 1, 0); LDA8(At, 1, 0); WAIT_V8(2); BAR8; WAIT_L8(0); MMA8(0, 0, At, B0); BAR8;
;     LDB8(B1, 1, 1); WAIT_V8(0); BAR8; WAIT_L8(0); MMA8(0, 1, At, B1); BAR8;
;     LDA8(At, 1, 1); BAR8; WAIT_L8(0); MMA8(1, 0, At, B0); MMA8(1, 1, At, B1); BAR8; }
;   if (wr == 0) BAR8;
;   __syncthreads();
;     ...
;   if (t < 256) {
;     float rs = 1.f;
	s_nop 0
	ds_read_b128 v[4:7], v159
	ds_read_b128 v[8:11], v159 offset:1024
	ds_read_b128 v[198:201], v159 offset:2048
	ds_read_b128 v[238:241], v159 offset:3072
	ds_read_b128 v[16:19], v156 offset:32768
	ds_read_b128 v[20:23], v156 offset:33792
	ds_read_b128 v[24:27], v154 offset:32768
	ds_read_b128 v[32:35], v154 offset:33792
	ds_read_b128 v[36:39], v153 offset:32768
	ds_read_b128 v[40:43], v153 offset:33792
	ds_read_b128 v[242:245], v152 offset:32768
	ds_read_b128 v[246:249], v152 offset:33792
	s_waitcnt vmcnt(2)
	s_barrier
	s_waitcnt lgkmcnt(0)
	v_mfma_f32_16x16x32_f16 v[12:15], v[16:19], v[4:7], v[128:131]
	v_mfma_f32_16x16x32_f16 v[104:107], v[20:23], v[8:11], v[12:15]
	v_mfma_f32_16x16x32_f16 v[12:15], v[16:19], v[198:201], v[124:127]
	v_mfma_f32_16x16x32_f16 v[116:119], v[20:23], v[238:241], v[12:15]
	v_mfma_f32_16x16x32_f16 v[12:15], v[24:27], v[4:7], v[120:123]
	v_mfma_f32_16x16x32_f16 v[100:103], v[32:35], v[8:11], v[12:15]
	v_mfma_f32_16x16x32_f16 v[12:15], v[24:27], v[198:201], v[132:135]
	v_mfma_f32_16x16x32_f16 v[108:111], v[32:35], v[238:241], v[12:15]
	v_mfma_f32_16x16x32_f16 v[12:15], v[36:39], v[4:7], v[112:115]
	v_mfma_f32_16x16x32_f16 v[92:95], v[40:43], v[8:11], v[12:15]
	v_mfma_f32_16x16x32_f16 v[12:15], v[36:39], v[198:201], v[170:173]
	v_mfma_f32_16x16x32_f16 v[96:99], v[40:43], v[238:241], v[12:15]
	v_mfma_f32_16x16x32_f16 v[12:15], v[242:245], v[4:7], v[206:209]
	v_mfma_f32_16x16x32_f16 v[84:87], v[246:249], v[8:11], v[12:15]
	v_mfma_f32_16x16x32_f16 v[12:15], v[242:245], v[198:201], v[210:213]
	v_mfma_f32_16x16x32_f16 v[88:91], v[246:249], v[238:241], v[12:15]
	s_barrier
	ds_read_b128 v[132:135], v158
	ds_read_b128 v[168:171], v158 offset:1024
	ds_read_b128 v[206:209], v158 offset:2048
	ds_read_b128 v[210:213], v158 offset:3072
	s_waitcnt vmcnt(0)
	s_barrier
	s_waitcnt lgkmcnt(0)
	v_mfma_f32_16x16x32_f16 v[12:15], v[16:19], v[132:135], v[214:217]
	v_mfma_f32_16x16x32_f16 v[16:19], v[16:19], v[206:209], v[174:177]
	v_mfma_f32_16x16x32_f16 v[12:15], v[20:23], v[168:171], v[12:15]
	v_mfma_f32_16x16x32_f16 v[28:31], v[20:23], v[210:213], v[16:19]
	v_mfma_f32_16x16x32_f16 v[16:19], v[24:27], v[132:135], v[178:181]
	v_mfma_f32_16x16x32_f16 v[20:23], v[24:27], v[206:209], v[182:185]
	v_mfma_f32_16x16x32_f16 v[16:19], v[32:35], v[168:171], v[16:19]
	v_mfma_f32_16x16x32_f16 v[32:35], v[32:35], v[210:213], v[20:23]
	v_mfma_f32_16x16x32_f16 v[20:23], v[36:39], v[132:135], v[80:83]
	v_mfma_f32_16x16x32_f16 v[24:27], v[36:39], v[206:209], v[76:79]
	v_mfma_f32_16x16x32_f16 v[20:23], v[40:43], v[168:171], v[20:23]
	v_mfma_f32_16x16x32_f16 v[36:39], v[40:43], v[210:213], v[24:27]
	v_mfma_f32_16x16x32_f16 v[24:27], v[242:245], v[132:135], v[72:75]
	v_mfma_f32_16x16x32_f16 v[40:43], v[242:245], v[206:209], v[68:71]
	v_mfma_f32_16x16x32_f16 v[24:27], v[246:249], v[168:171], v[24:27]
	v_mfma_f32_16x16x32_f16 v[40:43], v[246:249], v[210:213], v[40:43]
	s_barrier
	ds_read_b128 v[68:71], v156 offset:49152
	ds_read_b128 v[72:75], v156 offset:50176
	ds_read_b128 v[156:159], v154 offset:49152
	ds_read_b128 v[172:175], v154 offset:50176
	ds_read_b128 v[176:179], v153 offset:49152
	ds_read_b128 v[180:183], v153 offset:50176
	ds_read_b128 v[214:217], v152 offset:49152
	ds_read_b128 v[150:153], v152 offset:50176
	s_waitcnt lgkmcnt(0)
	v_mfma_f32_16x16x32_f16 v[64:67], v[68:71], v[4:7], v[64:67]
	v_mfma_f32_16x16x32_f16 v[56:59], v[156:159], v[4:7], v[56:59]
	v_mfma_f32_16x16x32_f16 v[48:51], v[176:179], v[4:7], v[48:51]
	v_mfma_f32_16x16x32_f16 v[4:7], v[214:217], v[4:7], v[136:139]
	v_mfma_f32_16x16x32_f16 v[128:131], v[72:75], v[8:11], v[64:67]
	v_mfma_f32_16x16x32_f16 v[60:63], v[68:71], v[198:201], v[60:63]
	v_mfma_f32_16x16x32_f16 v[120:123], v[172:175], v[8:11], v[56:59]
	v_mfma_f32_16x16x32_f16 v[52:55], v[156:159], v[198:201], v[52:55]
	v_mfma_f32_16x16x32_f16 v[80:83], v[180:183], v[8:11], v[48:51]
	v_mfma_f32_16x16x32_f16 v[44:47], v[176:179], v[198:201], v[44:47]
	v_mfma_f32_16x16x32_f16 v[8:11], v[150:153], v[8:11], v[4:7]
	v_mfma_f32_16x16x32_f16 v[4:7], v[214:217], v[198:201], v[140:143]
	v_mfma_f32_16x16x32_f16 v[124:127], v[72:75], v[238:241], v[60:63]
	v_mfma_f32_16x16x32_f16 v[112:115], v[172:175], v[238:241], v[52:55]
	v_mfma_f32_16x16x32_f16 v[76:79], v[180:183], v[238:241], v[44:47]
	v_mfma_f32_16x16x32_f16 v[4:7], v[150:153], v[238:241], v[4:7]
	v_mfma_f32_16x16x32_f16 v[44:47], v[68:71], v[132:135], v[160:163]
	v_mfma_f32_16x16x32_f16 v[48:51], v[68:71], v[206:209], v[164:167]
	v_mfma_f32_16x16x32_f16 v[52:55], v[156:159], v[206:209], v[218:221]
	v_mfma_f32_16x16x32_f16 v[56:59], v[176:179], v[206:209], v[186:189]
	v_mfma_f32_16x16x32_f16 v[44:47], v[72:75], v[168:171], v[44:47]
	v_mfma_f32_16x16x32_f16 v[60:63], v[72:75], v[210:213], v[48:51]
	v_mfma_f32_16x16x32_f16 v[48:51], v[156:159], v[132:135], v[202:205]
	v_mfma_f32_16x16x32_f16 v[64:67], v[172:175], v[210:213], v[52:55]
	v_mfma_f32_16x16x32_f16 v[52:55], v[176:179], v[132:135], v[230:233]
	v_mfma_f32_16x16x32_f16 v[68:71], v[180:183], v[210:213], v[56:59]
	v_mfma_f32_16x16x32_f16 v[56:59], v[214:217], v[132:135], v[190:193]
	v_mfma_f32_16x16x32_f16 v[72:75], v[214:217], v[206:209], v[194:197]
	v_mfma_f32_16x16x32_f16 v[48:51], v[172:175], v[168:171], v[48:51]
	v_mfma_f32_16x16x32_f16 v[52:55], v[180:183], v[168:171], v[52:55]
	v_mfma_f32_16x16x32_f16 v[56:59], v[150:153], v[168:171], v[56:59]
	v_mfma_f32_16x16x32_f16 v[72:75], v[150:153], v[210:213], v[72:75]
	s_movk_i32 s4, 0x100
	v_cmp_gt_u32_e32 vcc, s4, v3
	s_barrier
	s_and_saveexec_b64 s[4:5], vcc
	s_cbranch_execz .LBB0_195
	s_barrier

; #define LDA8(dst, b, h) _Pragma("unroll") for (int m = 0; m < 4; ++m) _Pragma("unroll") for (int k = 0; k < 2; ++k) \
;     dst[m][k] = *(const bf16x8*)((const char*)SA8(b, h) + lds_byte8(wr * 64 + m * 16 + fr, k * 32 + fq * 8))
; #define LDB8(dst, b, h) _Pragma("unroll") for (int n = 0; n < 2; ++n) _Pragma("unroll") for (int k = 0; k < 2; ++k) \
;     dst[n][k] = *(const bf16x8*)((const char*)SB8(b, h) + lds_byte8(wc * 32 + n * 16 + fr, k * 32 + fq * 8))
; #define WAIT_V8(n) asm volatile("s_waitcnt vmcnt(" #n ")" ::: "memory")
; #define WAIT_L8(n) asm volatile("s_waitcnt lgkmcnt(" #n ")" ::: "memory")
; #define BAR8 __builtin_amdgcn_s_barrier()
;     ...
;   { LDB8(B0, 0, 0); LDA8(At, 0, 0); STAGE8(SA8(1, 1), A, lda, brow + 128, nt - 1);
;     BAR8; WAIT_L8(0); MMA8(0, 0, At, B0); BAR8;
;     LDB8(B1, 0, 1); BAR8; WAIT_L8(0); MMA8(0, 1, At, B1); BAR8;
;     LDA8(At, 0, 1); WAIT_V8(4); BAR8; WAIT_L8(0); MMA8(1, 0, At, B0); MMA8(1, 1, At, B1); BAR8; }
.Lpk_exit_1:
	s_add_u32 s12, s12, 0x40780
	s_addc_u32 s13, s13, 0
	v_lshl_add_u64 v[132:133], s[12:13], 0, v[132:133]
	v_lshl_add_u64 v[0:1], v[0:1], 1, v[132:133]
	s_or_b32 m0, s100, 0xc000
	ds_read_b128 v[138:141], v171
	ds_read_b128 v[142:145], v171 offset:1024
	ds_read_b128 v[160:163], v171 offset:2048
	ds_read_b128 v[164:167], v171 offset:3072
	ds_read_b128 v[174:177], v156
	ds_read_b128 v[178:181], v156 offset:1024
	ds_read_b128 v[182:185], v154
	ds_read_b128 v[186:189], v154 offset:1024
	ds_read_b128 v[190:193], v153
	ds_read_b128 v[194:197], v153 offset:1024
	ds_read_b128 v[198:201], v152
	ds_read_b128 v[202:205], v152 offset:1024
	global_load_lds_dwordx4 v[0:1], off
	v_lshl_add_u64 v[0:1], s[12:13], 0, v[136:137]
	s_or_b32 m0, s100, 0xe000
	v_lshl_add_u64 v[0:1], v[134:135], 1, v[0:1]
	global_load_lds_dwordx4 v[0:1], off
	s_barrier
	s_waitcnt lgkmcnt(0)
	v_mfma_f32_16x16x32_f16 v[128:131], v[174:177], v[138:141], v[128:131]
	v_mfma_f32_16x16x32_f16 v[124:127], v[174:177], v[160:163], v[124:127]
	v_mfma_f32_16x16x32_f16 v[120:123], v[182:185], v[138:141], v[120:123]
	v_mfma_f32_16x16x32_f16 v[112:115], v[190:193], v[138:141], v[112:115]
	v_mfma_f32_16x16x32_f16 v[128:131], v[178:181], v[142:145], v[128:131]
	v_mfma_f32_16x16x32_f16 v[124:127], v[178:181], v[164:167], v[124:127]
	v_mfma_f32_16x16x32_f16 v[120:123], v[186:189], v[142:145], v[120:123]
	v_mfma_f32_16x16x32_f16 v[116:119], v[182:185], v[160:163], v[116:119]
	v_mfma_f32_16x16x32_f16 v[112:115], v[194:197], v[142:145], v[112:115]
	v_mfma_f32_16x16x32_f16 v[108:111], v[190:193], v[160:163], v[108:111]
	v_mfma_f32_16x16x32_f16 v[104:107], v[198:201], v[138:141], v[104:107]
	v_mfma_f32_16x16x32_f16 v[100:103], v[198:201], v[160:163], v[100:103]
	v_mfma_f32_16x16x32_f16 v[132:135], v[186:189], v[164:167], v[116:119]
	v_mfma_f32_16x16x32_f16 v[170:173], v[194:197], v[164:167], v[108:111]
	v_mfma_f32_16x16x32_f16 v[206:209], v[202:205], v[142:145], v[104:107]
	v_mfma_f32_16x16x32_f16 v[210:213], v[202:205], v[164:167], v[100:103]
	s_barrier
	s_nop 1
	ds_read_b128 v[100:103], v168
	ds_read_b128 v[104:107], v168 offset:1024
	ds_read_b128 v[108:111], v168 offset:2048
	ds_read_b128 v[116:119], v168 offset:3072
	s_barrier
	s_waitcnt lgkmcnt(0)
	v_mfma_f32_16x16x32_f16 v[80:83], v[190:193], v[100:103], v[80:83]
	v_mfma_f32_16x16x32_f16 v[76:79], v[190:193], v[108:111], v[76:79]
	v_mfma_f32_16x16x32_f16 v[72:75], v[198:201], v[100:103], v[72:75]
	v_mfma_f32_16x16x32_f16 v[68:71], v[198:201], v[108:111], v[68:71]
	v_mfma_f32_16x16x32_f16 v[96:99], v[174:177], v[100:103], v[96:99]
	v_mfma_f32_16x16x32_f16 v[92:95], v[174:177], v[108:111], v[92:95]
	v_mfma_f32_16x16x32_f16 v[88:91], v[182:185], v[100:103], v[88:91]
	v_mfma_f32_16x16x32_f16 v[84:87], v[182:185], v[108:111], v[84:87]
	v_mfma_f32_16x16x32_f16 v[80:83], v[194:197], v[104:107], v[80:83]
	v_mfma_f32_16x16x32_f16 v[76:79], v[194:197], v[116:119], v[76:79]
	v_mfma_f32_16x16x32_f16 v[72:75], v[202:205], v[104:107], v[72:75]
	v_mfma_f32_16x16x32_f16 v[68:71], v[202:205], v[116:119], v[68:71]
	v_mfma_f32_16x16x32_f16 v[214:217], v[178:181], v[104:107], v[96:99]
	v_mfma_f32_16x16x32_f16 v[174:177], v[178:181], v[116:119], v[92:95]
	v_mfma_f32_16x16x32_f16 v[178:181], v[186:189], v[104:107], v[88:91]
	v_mfma_f32_16x16x32_f16 v[182:185], v[186:189], v[116:119], v[84:87]
	s_barrier
	s_nop 0
	ds_read_b128 v[84:87], v156 offset:16384
	ds_read_b128 v[88:91], v156 offset:17408
	ds_read_b128 v[92:95], v154 offset:16384
	ds_read_b128 v[96:99], v154 offset:17408
	ds_read_b128 v[186:189], v153 offset:16384
	ds_read_b128 v[190:193], v153 offset:17408
	ds_read_b128 v[194:197], v152 offset:16384
	ds_read_b128 v[198:201], v152 offset:17408
	s_waitcnt vmcnt(4)
	s_barrier
	s_waitcnt lgkmcnt(0)
	v_mfma_f32_16x16x32_f16 v[64:67], v[84:87], v[138:141], v[64:67]
	v_mfma_f32_16x16x32_f16 v[60:63], v[84:87], v[160:163], v[60:63]
	v_mfma_f32_16x16x32_f16 v[56:59], v[92:95], v[138:141], v[56:59]
	v_mfma_f32_16x16x32_f16 v[52:55], v[92:95], v[160:163], v[52:55]
	v_mfma_f32_16x16x32_f16 v[48:51], v[186:189], v[138:141], v[48:51]
	v_mfma_f32_16x16x32_f16 v[44:47], v[186:189], v[160:163], v[44:47]
	v_mfma_f32_16x16x32_f16 v[40:43], v[194:197], v[138:141], v[40:43]
	v_mfma_f32_16x16x32_f16 v[36:39], v[194:197], v[160:163], v[36:39]
	v_mfma_f32_16x16x32_f16 v[64:67], v[88:91], v[142:145], v[64:67]
	v_mfma_f32_16x16x32_f16 v[60:63], v[88:91], v[164:167], v[60:63]
	v_mfma_f32_16x16x32_f16 v[56:59], v[96:99], v[142:145], v[56:59]
	v_mfma_f32_16x16x32_f16 v[52:55], v[96:99], v[164:167], v[52:55]
	v_mfma_f32_16x16x32_f16 v[48:51], v[190:193], v[142:145], v[48:51]
	v_mfma_f32_16x16x32_f16 v[44:47], v[190:193], v[164:167], v[44:47]
	v_mfma_f32_16x16x32_f16 v[40:43], v[198:201], v[142:145], v[40:43]
	v_mfma_f32_16x16x32_f16 v[36:39], v[198:201], v[164:167], v[36:39]
	v_mfma_f32_16x16x32_f16 v[32:35], v[84:87], v[100:103], v[32:35]
	v_mfma_f32_16x16x32_f16 v[28:31], v[84:87], v[108:111], v[28:31]
	v_mfma_f32_16x16x32_f16 v[24:27], v[92:95], v[100:103], v[24:27]
	v_mfma_f32_16x16x32_f16 v[20:23], v[92:95], v[108:111], v[20:23]
	v_mfma_f32_16x16x32_f16 v[16:19], v[186:189], v[100:103], v[16:19]
	v_mfma_f32_16x16x32_f16 v[12:15], v[186:189], v[108:111], v[12:15]
	v_mfma_f32_16x16x32_f16 v[8:11], v[194:197], v[100:103], v[8:11]
	v_mfma_f32_16x16x32_f16 v[4:7], v[194:197], v[108:111], v[4:7]
	v_mfma_f32_16x16x32_f16 v[136:139], v[88:91], v[104:107], v[32:35]
	v_mfma_f32_16x16x32_f16 v[140:143], v[88:91], v[116:119], v[28:31]
	v_mfma_f32_16x16x32_f16 v[160:163], v[96:99], v[104:107], v[24:27]
	v_mfma_f32_16x16x32_f16 v[164:167], v[96:99], v[116:119], v[20:23]
	v_mfma_f32_16x16x32_f16 v[202:205], v[190:193], v[104:107], v[16:19]
	v_mfma_f32_16x16x32_f16 v[186:189], v[190:193], v[116:119], v[12:15]
	v_mfma_f32_16x16x32_f16 v[190:193], v[198:201], v[104:107], v[8:11]
	v_mfma_f32_16x16x32_f16 v[194:197], v[198:201], v[116:119], v[4:7]
	s_barrier
; #define LDA8(dst, b, h) _Pragma("unroll") for (int m = 0; m < 4; ++m) _Pragma("unroll") for (int k = 0; k < 2; ++k) \
;     dst[m][k] = *(const bf16x8*)((const char*)SA8(b, h) + lds_byte8(wr * 64 + m * 16 + fr, k * 32 + fq * 8))
; #define LDB8(dst, b, h) _Pragma("unroll") for (int n = 0; n < 2; ++n) _Pragma("unroll") for (int k = 0; k < 2; ++k) \
;     dst[n][k] = *(const bf16x8*)((const char*)SB8(b, h) + lds_byte8(wc * 32 + n * 16 + fr, k * 32 + fq * 8))
; #define WAIT_V8(n) asm volatile("s_waitcnt vmcnt(" #n ")" ::: "memory")
; #define WAIT_L8(n) asm volatile("s_waitcnt lgkmcnt(" #n ")" ::: "memory")
; #define BAR8 __builtin_amdgcn_s_barrier()
;     ...
;   { LDB8(B0, 1, 0); LDA8(At, 1, 0); WAIT_V8(2); BAR8; WAIT_L8(0); MMA8(0, 0, At, B0); BAR8;
;     LDB8(B1, 1, 1); WAIT_V8(0); BAR8; WAIT_L8(0); MMA8(0, 1, At, B1); BAR8;
;     LDA8(At, 1, 1); BAR8; WAIT_L8(0); MMA8(1, 0, At, B0); MMA8(1, 1, At, B1); BAR8; }
;   if (wr == 0) BAR8;
;   __syncthreads();
	ds_read_b128 v[198:201], v159
	ds_read_b128 v[218:221], v159 offset:1024
	ds_read_b128 v[230:233], v159 offset:2048
	ds_read_b128 v[238:241], v159 offset:3072
	ds_read_b128 v[8:11], v156 offset:32768
	ds_read_b128 v[12:15], v156 offset:33792
	ds_read_b128 v[16:19], v154 offset:32768
	ds_read_b128 v[24:27], v154 offset:33792
	ds_read_b128 v[28:31], v153 offset:32768
	ds_read_b128 v[32:35], v153 offset:33792
	ds_read_b128 v[242:245], v152 offset:32768
	ds_read_b128 v[246:249], v152 offset:33792
	s_waitcnt vmcnt(2)
	s_barrier
	s_waitcnt lgkmcnt(0)
	v_mfma_f32_16x16x32_f16 v[4:7], v[8:11], v[198:201], v[128:131]
	v_mfma_f32_16x16x32_f16 v[104:107], v[12:15], v[218:221], v[4:7]
	v_mfma_f32_16x16x32_f16 v[4:7], v[8:11], v[230:233], v[124:127]
	v_mfma_f32_16x16x32_f16 v[116:119], v[12:15], v[238:241], v[4:7]
	v_mfma_f32_16x16x32_f16 v[4:7], v[16:19], v[198:201], v[120:123]
	v_mfma_f32_16x16x32_f16 v[100:103], v[24:27], v[218:221], v[4:7]
	v_mfma_f32_16x16x32_f16 v[4:7], v[16:19], v[230:233], v[132:135]
	v_mfma_f32_16x16x32_f16 v[108:111], v[24:27], v[238:241], v[4:7]
	v_mfma_f32_16x16x32_f16 v[4:7], v[28:31], v[198:201], v[112:115]
	v_mfma_f32_16x16x32_f16 v[92:95], v[32:35], v[218:221], v[4:7]
	v_mfma_f32_16x16x32_f16 v[4:7], v[28:31], v[230:233], v[170:173]
	v_mfma_f32_16x16x32_f16 v[96:99], v[32:35], v[238:241], v[4:7]
	v_mfma_f32_16x16x32_f16 v[4:7], v[242:245], v[198:201], v[206:209]
	v_mfma_f32_16x16x32_f16 v[84:87], v[246:249], v[218:221], v[4:7]
	v_mfma_f32_16x16x32_f16 v[4:7], v[242:245], v[230:233], v[210:213]
	v_mfma_f32_16x16x32_f16 v[88:91], v[246:249], v[238:241], v[4:7]
	s_barrier
	ds_read_b128 v[132:135], v157
	ds_read_b128 v[168:171], v157 offset:1024
	ds_read_b128 v[206:209], v157 offset:2048
	ds_read_b128 v[210:213], v157 offset:3072
	s_waitcnt vmcnt(0)
	s_barrier
	s_waitcnt lgkmcnt(0)
	v_mfma_f32_16x16x32_f16 v[4:7], v[8:11], v[132:135], v[214:217]
	v_mfma_f32_16x16x32_f16 v[8:11], v[8:11], v[206:209], v[174:177]
	v_mfma_f32_16x16x32_f16 v[4:7], v[12:15], v[168:171], v[4:7]
	v_mfma_f32_16x16x32_f16 v[20:23], v[12:15], v[210:213], v[8:11]
	v_mfma_f32_16x16x32_f16 v[8:11], v[16:19], v[132:135], v[178:181]
	v_mfma_f32_16x16x32_f16 v[12:15], v[16:19], v[206:209], v[182:185]
	v_mfma_f32_16x16x32_f16 v[8:11], v[24:27], v[168:171], v[8:11]
	v_mfma_f32_16x16x32_f16 v[24:27], v[24:27], v[210:213], v[12:15]
	v_mfma_f32_16x16x32_f16 v[12:15], v[28:31], v[132:135], v[80:83]
	v_mfma_f32_16x16x32_f16 v[16:19], v[28:31], v[206:209], v[76:79]
	v_mfma_f32_16x16x32_f16 v[12:15], v[32:35], v[168:171], v[12:15]
	v_mfma_f32_16x16x32_f16 v[28:31], v[32:35], v[210:213], v[16:19]
	v_mfma_f32_16x16x32_f16 v[16:19], v[242:245], v[132:135], v[72:75]
	v_mfma_f32_16x16x32_f16 v[32:35], v[242:245], v[206:209], v[68:71]
	v_mfma_f32_16x16x32_f16 v[16:19], v[246:249], v[168:171], v[16:19]
	v_mfma_f32_16x16x32_f16 v[32:35], v[246:249], v[210:213], v[32:35]
	s_barrier
	ds_read_b128 v[172:175], v156 offset:49152
	ds_read_b128 v[156:159], v156 offset:50176
	ds_read_b128 v[176:179], v154 offset:49152
	ds_read_b128 v[180:183], v154 offset:50176
	ds_read_b128 v[214:217], v153 offset:49152
	ds_read_b128 v[242:245], v153 offset:50176
	ds_read_b128 v[246:249], v152 offset:49152
	ds_read_b128 v[150:153], v152 offset:50176
	s_waitcnt lgkmcnt(0)
	v_mfma_f32_16x16x32_f16 v[64:67], v[172:175], v[198:201], v[64:67]
	v_mfma_f32_16x16x32_f16 v[60:63], v[172:175], v[230:233], v[60:63]
	v_mfma_f32_16x16x32_f16 v[56:59], v[176:179], v[198:201], v[56:59]
	v_mfma_f32_16x16x32_f16 v[52:55], v[176:179], v[230:233], v[52:55]
	v_mfma_f32_16x16x32_f16 v[48:51], v[214:217], v[198:201], v[48:51]
	v_mfma_f32_16x16x32_f16 v[44:47], v[214:217], v[230:233], v[44:47]
	v_mfma_f32_16x16x32_f16 v[40:43], v[246:249], v[198:201], v[40:43]
	v_mfma_f32_16x16x32_f16 v[36:39], v[246:249], v[230:233], v[36:39]
	v_mfma_f32_16x16x32_f16 v[128:131], v[156:159], v[218:221], v[64:67]
	v_mfma_f32_16x16x32_f16 v[124:127], v[156:159], v[238:241], v[60:63]
	v_mfma_f32_16x16x32_f16 v[120:123], v[180:183], v[218:221], v[56:59]
	v_mfma_f32_16x16x32_f16 v[112:115], v[180:183], v[238:241], v[52:55]
	v_mfma_f32_16x16x32_f16 v[80:83], v[242:245], v[218:221], v[48:51]
	v_mfma_f32_16x16x32_f16 v[76:79], v[242:245], v[238:241], v[44:47]
	v_mfma_f32_16x16x32_f16 v[72:75], v[150:153], v[218:221], v[40:43]
	v_mfma_f32_16x16x32_f16 v[68:71], v[150:153], v[238:241], v[36:39]
	v_mfma_f32_16x16x32_f16 v[40:43], v[172:175], v[206:209], v[140:143]
	v_mfma_f32_16x16x32_f16 v[44:47], v[176:179], v[206:209], v[164:167]
	v_mfma_f32_16x16x32_f16 v[48:51], v[214:217], v[206:209], v[186:189]
	v_mfma_f32_16x16x32_f16 v[36:39], v[172:175], v[132:135], v[136:139]
	v_mfma_f32_16x16x32_f16 v[52:55], v[156:159], v[210:213], v[40:43]
	v_mfma_f32_16x16x32_f16 v[40:43], v[176:179], v[132:135], v[160:163]
	v_mfma_f32_16x16x32_f16 v[56:59], v[180:183], v[210:213], v[44:47]
	v_mfma_f32_16x16x32_f16 v[44:47], v[214:217], v[132:135], v[202:205]
	v_mfma_f32_16x16x32_f16 v[60:63], v[242:245], v[210:213], v[48:51]
	v_mfma_f32_16x16x32_f16 v[48:51], v[246:249], v[132:135], v[190:193]
	v_mfma_f32_16x16x32_f16 v[64:67], v[246:249], v[206:209], v[194:197]
	v_mfma_f32_16x16x32_f16 v[36:39], v[156:159], v[168:171], v[36:39]
	v_mfma_f32_16x16x32_f16 v[40:43], v[180:183], v[168:171], v[40:43]
	v_mfma_f32_16x16x32_f16 v[44:47], v[242:245], v[168:171], v[44:47]
	v_mfma_f32_16x16x32_f16 v[48:51], v[150:153], v[168:171], v[48:51]
	v_mfma_f32_16x16x32_f16 v[64:67], v[150:153], v[210:213], v[64:67]
	s_movk_i32 s1, 0x100
	v_cmp_gt_u32_e32 vcc, s1, v3
	s_barrier
	s_and_saveexec_b64 s[12:13], vcc
	s_cbranch_execz .LBB0_245
	s_barrier

; #define LDA8(dst, b, h) _Pragma("unroll") for (int m = 0; m < 4; ++m) _Pragma("unroll") for (int k = 0; k < 2; ++k) \
;     dst[m][k] = *(const bf16x8*)((const char*)SA8(b, h) + lds_byte8(wr * 64 + m * 16 + fr, k * 32 + fq * 8))
; #define LDB8(dst, b, h) _Pragma("unroll") for (int n = 0; n < 2; ++n) _Pragma("unroll") for (int k = 0; k < 2; ++k) \
;     dst[n][k] = *(const bf16x8*)((const char*)SB8(b, h) + lds_byte8(wc * 32 + n * 16 + fr, k * 32 + fq * 8))
; #define WAIT_V8(n) asm volatile("s_waitcnt vmcnt(" #n ")" ::: "memory")
; #define WAIT_L8(n) asm volatile("s_waitcnt lgkmcnt(" #n ")" ::: "memory")
; #define BAR8 __builtin_amdgcn_s_barrier()
;     ...
;   { LDB8(B0, 0, 0); LDA8(At, 0, 0); STAGE8(SA8(1, 1), A, lda, brow + 128, nt - 1);
;     BAR8; WAIT_L8(0); MMA8(0, 0, At, B0); BAR8;
;     LDB8(B1, 0, 1); BAR8; WAIT_L8(0); MMA8(0, 1, At, B1); BAR8;
;     LDA8(At, 0, 1); WAIT_V8(4); BAR8; WAIT_L8(0); MMA8(1, 0, At, B0); MMA8(1, 1, At, B1); BAR8; }
.Lpk_exit_2:
	s_add_u32 s2, s2, s27
	s_addc_u32 s3, s3, 0
	s_add_u32 s2, s2, 0x6000780
	s_addc_u32 s3, s3, 0
	v_lshl_add_u64 v[136:137], v[136:137], 1, s[2:3]
	v_lshl_add_u64 v[0:1], v[0:1], 1, v[136:137]
	s_or_b32 m0, s100, 0xc000
	ds_read_b128 v[138:141], v171
	ds_read_b128 v[142:145], v171 offset:1024
	ds_read_b128 v[162:165], v171 offset:2048
	ds_read_b128 v[168:171], v171 offset:3072
	ds_read_b128 v[174:177], v156
	ds_read_b128 v[178:181], v156 offset:1024
	ds_read_b128 v[182:185], v155
	ds_read_b128 v[186:189], v155 offset:1024
	ds_read_b128 v[190:193], v154
	ds_read_b128 v[194:197], v154 offset:1024
	ds_read_b128 v[198:201], v153
	ds_read_b128 v[202:205], v153 offset:1024
	global_load_lds_dwordx4 v[0:1], off
	v_lshl_add_u64 v[0:1], v[134:135], 1, s[2:3]
	s_or_b32 m0, s100, 0xe000
	v_lshl_add_u64 v[0:1], v[132:133], 1, v[0:1]
	global_load_lds_dwordx4 v[0:1], off
	s_barrier
	s_waitcnt lgkmcnt(0)
	v_mfma_f32_16x16x32_bf16 v[128:131], v[174:177], v[138:141], v[128:131]
	v_mfma_f32_16x16x32_bf16 v[124:127], v[174:177], v[162:165], v[124:127]
	v_mfma_f32_16x16x32_bf16 v[120:123], v[182:185], v[138:141], v[120:123]
	v_mfma_f32_16x16x32_bf16 v[112:115], v[190:193], v[138:141], v[112:115]
	v_mfma_f32_16x16x32_bf16 v[128:131], v[178:181], v[142:145], v[128:131]
	v_mfma_f32_16x16x32_bf16 v[124:127], v[178:181], v[168:171], v[124:127]
	v_mfma_f32_16x16x32_bf16 v[120:123], v[186:189], v[142:145], v[120:123]
	v_mfma_f32_16x16x32_bf16 v[116:119], v[182:185], v[162:165], v[116:119]
	v_mfma_f32_16x16x32_bf16 v[112:115], v[194:197], v[142:145], v[112:115]
	v_mfma_f32_16x16x32_bf16 v[108:111], v[190:193], v[162:165], v[108:111]
	v_mfma_f32_16x16x32_bf16 v[104:107], v[198:201], v[138:141], v[104:107]
	v_mfma_f32_16x16x32_bf16 v[100:103], v[198:201], v[162:165], v[100:103]
	v_mfma_f32_16x16x32_bf16 v[132:135], v[186:189], v[168:171], v[116:119]
	v_mfma_f32_16x16x32_bf16 v[206:209], v[194:197], v[168:171], v[108:111]
	v_mfma_f32_16x16x32_bf16 v[210:213], v[202:205], v[142:145], v[104:107]
	v_mfma_f32_16x16x32_bf16 v[214:217], v[202:205], v[168:171], v[100:103]
	s_barrier
	s_nop 1
	ds_read_b128 v[100:103], v167
	ds_read_b128 v[104:107], v167 offset:1024
	ds_read_b128 v[108:111], v167 offset:2048
	ds_read_b128 v[116:119], v167 offset:3072
	s_barrier
	s_waitcnt lgkmcnt(0)
	v_mfma_f32_16x16x32_bf16 v[80:83], v[190:193], v[100:103], v[80:83]
	v_mfma_f32_16x16x32_bf16 v[76:79], v[190:193], v[108:111], v[76:79]
	v_mfma_f32_16x16x32_bf16 v[72:75], v[198:201], v[100:103], v[72:75]
	v_mfma_f32_16x16x32_bf16 v[68:71], v[198:201], v[108:111], v[68:71]
	v_mfma_f32_16x16x32_bf16 v[96:99], v[174:177], v[100:103], v[96:99]
	v_mfma_f32_16x16x32_bf16 v[92:95], v[174:177], v[108:111], v[92:95]
	v_mfma_f32_16x16x32_bf16 v[88:91], v[182:185], v[100:103], v[88:91]
	v_mfma_f32_16x16x32_bf16 v[84:87], v[182:185], v[108:111], v[84:87]
	v_mfma_f32_16x16x32_bf16 v[80:83], v[194:197], v[104:107], v[80:83]
	v_mfma_f32_16x16x32_bf16 v[76:79], v[194:197], v[116:119], v[76:79]
	v_mfma_f32_16x16x32_bf16 v[72:75], v[202:205], v[104:107], v[72:75]
	v_mfma_f32_16x16x32_bf16 v[68:71], v[202:205], v[116:119], v[68:71]
	v_mfma_f32_16x16x32_bf16 v[218:221], v[178:181], v[104:107], v[96:99]
	v_mfma_f32_16x16x32_bf16 v[172:175], v[178:181], v[116:119], v[92:95]
	v_mfma_f32_16x16x32_bf16 v[176:179], v[186:189], v[104:107], v[88:91]
	v_mfma_f32_16x16x32_bf16 v[180:183], v[186:189], v[116:119], v[84:87]
	s_barrier
	s_nop 0
	ds_read_b128 v[84:87], v156 offset:16384
	ds_read_b128 v[88:91], v156 offset:17408
	ds_read_b128 v[92:95], v155 offset:16384
	ds_read_b128 v[96:99], v155 offset:17408
	ds_read_b128 v[184:187], v154 offset:16384
	ds_read_b128 v[188:191], v154 offset:17408
	ds_read_b128 v[192:195], v153 offset:16384
	ds_read_b128 v[196:199], v153 offset:17408
	s_waitcnt vmcnt(4)
	s_barrier
	s_waitcnt lgkmcnt(0)
	v_mfma_f32_16x16x32_bf16 v[64:67], v[84:87], v[138:141], v[64:67]
	v_mfma_f32_16x16x32_bf16 v[60:63], v[84:87], v[162:165], v[60:63]
	v_mfma_f32_16x16x32_bf16 v[56:59], v[92:95], v[138:141], v[56:59]
	v_mfma_f32_16x16x32_bf16 v[52:55], v[92:95], v[162:165], v[52:55]
	v_mfma_f32_16x16x32_bf16 v[48:51], v[184:187], v[138:141], v[48:51]
	v_mfma_f32_16x16x32_bf16 v[44:47], v[184:187], v[162:165], v[44:47]
	v_mfma_f32_16x16x32_bf16 v[40:43], v[192:195], v[138:141], v[40:43]
	v_mfma_f32_16x16x32_bf16 v[36:39], v[192:195], v[162:165], v[36:39]
	v_mfma_f32_16x16x32_bf16 v[64:67], v[88:91], v[142:145], v[64:67]
	v_mfma_f32_16x16x32_bf16 v[60:63], v[88:91], v[168:171], v[60:63]
	v_mfma_f32_16x16x32_bf16 v[56:59], v[96:99], v[142:145], v[56:59]
	v_mfma_f32_16x16x32_bf16 v[52:55], v[96:99], v[168:171], v[52:55]
	v_mfma_f32_16x16x32_bf16 v[48:51], v[188:191], v[142:145], v[48:51]
	v_mfma_f32_16x16x32_bf16 v[44:47], v[188:191], v[168:171], v[44:47]
	v_mfma_f32_16x16x32_bf16 v[40:43], v[196:199], v[142:145], v[40:43]
	v_mfma_f32_16x16x32_bf16 v[36:39], v[196:199], v[168:171], v[36:39]
	v_mfma_f32_16x16x32_bf16 v[32:35], v[84:87], v[100:103], v[32:35]
	v_mfma_f32_16x16x32_bf16 v[28:31], v[84:87], v[108:111], v[28:31]
	v_mfma_f32_16x16x32_bf16 v[24:27], v[92:95], v[100:103], v[24:27]
	v_mfma_f32_16x16x32_bf16 v[20:23], v[92:95], v[108:111], v[20:23]
	v_mfma_f32_16x16x32_bf16 v[16:19], v[184:187], v[100:103], v[16:19]
	v_mfma_f32_16x16x32_bf16 v[12:15], v[184:187], v[108:111], v[12:15]
	v_mfma_f32_16x16x32_bf16 v[8:11], v[192:195], v[100:103], v[8:11]
	v_mfma_f32_16x16x32_bf16 v[4:7], v[192:195], v[108:111], v[4:7]
	v_mfma_f32_16x16x32_bf16 v[136:139], v[88:91], v[104:107], v[32:35]
	v_mfma_f32_16x16x32_bf16 v[140:143], v[88:91], v[116:119], v[28:31]
	v_mfma_f32_16x16x32_bf16 v[162:165], v[96:99], v[104:107], v[24:27]
	v_mfma_f32_16x16x32_bf16 v[166:169], v[96:99], v[116:119], v[20:23]
	v_mfma_f32_16x16x32_bf16 v[200:203], v[188:191], v[104:107], v[16:19]
	v_mfma_f32_16x16x32_bf16 v[184:187], v[188:191], v[116:119], v[12:15]
	v_mfma_f32_16x16x32_bf16 v[188:191], v[196:199], v[104:107], v[8:11]
	v_mfma_f32_16x16x32_bf16 v[192:195], v[196:199], v[116:119], v[4:7]
	s_barrier
; #define LDA8(dst, b, h) _Pragma("unroll") for (int m = 0; m < 4; ++m) _Pragma("unroll") for (int k = 0; k < 2; ++k) \
;     dst[m][k] = *(const bf16x8*)((const char*)SA8(b, h) + lds_byte8(wr * 64 + m * 16 + fr, k * 32 + fq * 8))
; #define LDB8(dst, b, h) _Pragma("unroll") for (int n = 0; n < 2; ++n) _Pragma("unroll") for (int k = 0; k < 2; ++k) \
;     dst[n][k] = *(const bf16x8*)((const char*)SB8(b, h) + lds_byte8(wc * 32 + n * 16 + fr, k * 32 + fq * 8))
; #define WAIT_V8(n) asm volatile("s_waitcnt vmcnt(" #n ")" ::: "memory")
; #define WAIT_L8(n) asm volatile("s_waitcnt lgkmcnt(" #n ")" ::: "memory")
; #define BAR8 __builtin_amdgcn_s_barrier()
;     ...
;   { LDB8(B0, 1, 0); LDA8(At, 1, 0); WAIT_V8(2); BAR8; WAIT_L8(0); MMA8(0, 0, At, B0); BAR8;
;     LDB8(B1, 1, 1); WAIT_V8(0); BAR8; WAIT_L8(0); MMA8(0, 1, At, B1); BAR8;
;     LDA8(At, 1, 1); BAR8; WAIT_L8(0); MMA8(1, 0, At, B0); MMA8(1, 1, At, B1); BAR8; }
;   if (wr == 0) BAR8;
;   __syncthreads();
	ds_read_b128 v[196:199], v160
	ds_read_b128 v[230:233], v160 offset:1024
	ds_read_b128 v[238:241], v160 offset:2048
	ds_read_b128 v[242:245], v160 offset:3072
	ds_read_b128 v[8:11], v156 offset:32768
	ds_read_b128 v[12:15], v156 offset:33792
	ds_read_b128 v[16:19], v155 offset:32768
	ds_read_b128 v[24:27], v155 offset:33792
	ds_read_b128 v[28:31], v154 offset:32768
	ds_read_b128 v[32:35], v154 offset:33792
	ds_read_b128 v[246:249], v153 offset:32768
	ds_read_b128 v[226:229], v153 offset:33792
	s_waitcnt vmcnt(2)
	s_barrier
	s_waitcnt lgkmcnt(0)
	v_mfma_f32_16x16x32_bf16 v[4:7], v[8:11], v[196:199], v[128:131]
	v_mfma_f32_16x16x32_bf16 v[104:107], v[12:15], v[230:233], v[4:7]
	v_mfma_f32_16x16x32_bf16 v[4:7], v[8:11], v[238:241], v[124:127]
	v_mfma_f32_16x16x32_bf16 v[116:119], v[12:15], v[242:245], v[4:7]
	v_mfma_f32_16x16x32_bf16 v[4:7], v[16:19], v[196:199], v[120:123]
	v_mfma_f32_16x16x32_bf16 v[100:103], v[24:27], v[230:233], v[4:7]
	v_mfma_f32_16x16x32_bf16 v[4:7], v[16:19], v[238:241], v[132:135]
	v_mfma_f32_16x16x32_bf16 v[108:111], v[24:27], v[242:245], v[4:7]
	v_mfma_f32_16x16x32_bf16 v[4:7], v[28:31], v[196:199], v[112:115]
	v_mfma_f32_16x16x32_bf16 v[92:95], v[32:35], v[230:233], v[4:7]
	v_mfma_f32_16x16x32_bf16 v[4:7], v[28:31], v[238:241], v[206:209]
	v_mfma_f32_16x16x32_bf16 v[96:99], v[32:35], v[242:245], v[4:7]
	v_mfma_f32_16x16x32_bf16 v[4:7], v[246:249], v[196:199], v[210:213]
	v_mfma_f32_16x16x32_bf16 v[84:87], v[226:229], v[230:233], v[4:7]
	v_mfma_f32_16x16x32_bf16 v[4:7], v[246:249], v[238:241], v[214:217]
	v_mfma_f32_16x16x32_bf16 v[88:91], v[226:229], v[242:245], v[4:7]
	s_barrier
	ds_read_b128 v[132:135], v158
	ds_read_b128 v[204:207], v158 offset:1024
	ds_read_b128 v[208:211], v158 offset:2048
	ds_read_b128 v[158:161], v158 offset:3072
	s_waitcnt vmcnt(0)
	s_barrier
	s_waitcnt lgkmcnt(0)
	v_mfma_f32_16x16x32_bf16 v[4:7], v[8:11], v[132:135], v[218:221]
	v_mfma_f32_16x16x32_bf16 v[8:11], v[8:11], v[208:211], v[172:175]
	v_mfma_f32_16x16x32_bf16 v[4:7], v[12:15], v[204:207], v[4:7]
	v_mfma_f32_16x16x32_bf16 v[20:23], v[12:15], v[158:161], v[8:11]
	v_mfma_f32_16x16x32_bf16 v[8:11], v[16:19], v[132:135], v[176:179]
	v_mfma_f32_16x16x32_bf16 v[12:15], v[16:19], v[208:211], v[180:183]
	v_mfma_f32_16x16x32_bf16 v[8:11], v[24:27], v[204:207], v[8:11]
	v_mfma_f32_16x16x32_bf16 v[24:27], v[24:27], v[158:161], v[12:15]
	v_mfma_f32_16x16x32_bf16 v[12:15], v[28:31], v[132:135], v[80:83]
	v_mfma_f32_16x16x32_bf16 v[16:19], v[28:31], v[208:211], v[76:79]
	v_mfma_f32_16x16x32_bf16 v[12:15], v[32:35], v[204:207], v[12:15]
	v_mfma_f32_16x16x32_bf16 v[28:31], v[32:35], v[158:161], v[16:19]
	v_mfma_f32_16x16x32_bf16 v[16:19], v[246:249], v[132:135], v[72:75]
	v_mfma_f32_16x16x32_bf16 v[32:35], v[246:249], v[208:211], v[68:71]
	v_mfma_f32_16x16x32_bf16 v[16:19], v[226:229], v[204:207], v[16:19]
	v_mfma_f32_16x16x32_bf16 v[32:35], v[226:229], v[158:161], v[32:35]
	s_barrier
	ds_read_b128 v[170:173], v156 offset:49152
	ds_read_b128 v[174:177], v156 offset:50176
	ds_read_b128 v[178:181], v155 offset:49152
	ds_read_b128 v[212:215], v155 offset:50176
	ds_read_b128 v[216:219], v154 offset:49152
	ds_read_b128 v[154:157], v154 offset:50176
	ds_read_b128 v[220:223], v153 offset:49152
	ds_read_b128 v[150:153], v153 offset:50176
	s_waitcnt lgkmcnt(0)
	v_mfma_f32_16x16x32_bf16 v[64:67], v[170:173], v[196:199], v[64:67]
	v_mfma_f32_16x16x32_bf16 v[60:63], v[170:173], v[238:241], v[60:63]
	v_mfma_f32_16x16x32_bf16 v[56:59], v[178:181], v[196:199], v[56:59]
	v_mfma_f32_16x16x32_bf16 v[52:55], v[178:181], v[238:241], v[52:55]
	v_mfma_f32_16x16x32_bf16 v[48:51], v[216:219], v[196:199], v[48:51]
	v_mfma_f32_16x16x32_bf16 v[44:47], v[216:219], v[238:241], v[44:47]
	v_mfma_f32_16x16x32_bf16 v[40:43], v[220:223], v[196:199], v[40:43]
	v_mfma_f32_16x16x32_bf16 v[36:39], v[220:223], v[238:241], v[36:39]
	v_mfma_f32_16x16x32_bf16 v[128:131], v[174:177], v[230:233], v[64:67]
	v_mfma_f32_16x16x32_bf16 v[124:127], v[174:177], v[242:245], v[60:63]
	v_mfma_f32_16x16x32_bf16 v[120:123], v[212:215], v[230:233], v[56:59]
	v_mfma_f32_16x16x32_bf16 v[112:115], v[212:215], v[242:245], v[52:55]
	v_mfma_f32_16x16x32_bf16 v[80:83], v[154:157], v[230:233], v[48:51]
	v_mfma_f32_16x16x32_bf16 v[76:79], v[154:157], v[242:245], v[44:47]
	v_mfma_f32_16x16x32_bf16 v[72:75], v[150:153], v[230:233], v[40:43]
	v_mfma_f32_16x16x32_bf16 v[68:71], v[150:153], v[242:245], v[36:39]
	v_mfma_f32_16x16x32_bf16 v[40:43], v[170:173], v[208:211], v[140:143]
	v_mfma_f32_16x16x32_bf16 v[44:47], v[178:181], v[208:211], v[166:169]
	v_mfma_f32_16x16x32_bf16 v[48:51], v[216:219], v[208:211], v[184:187]
	v_mfma_f32_16x16x32_bf16 v[36:39], v[170:173], v[132:135], v[136:139]
	v_mfma_f32_16x16x32_bf16 v[52:55], v[174:177], v[158:161], v[40:43]
	v_mfma_f32_16x16x32_bf16 v[40:43], v[178:181], v[132:135], v[162:165]
	v_mfma_f32_16x16x32_bf16 v[56:59], v[212:215], v[158:161], v[44:47]
	v_mfma_f32_16x16x32_bf16 v[44:47], v[216:219], v[132:135], v[200:203]
	v_mfma_f32_16x16x32_bf16 v[60:63], v[154:157], v[158:161], v[48:51]
	v_mfma_f32_16x16x32_bf16 v[48:51], v[220:223], v[132:135], v[188:191]
	v_mfma_f32_16x16x32_bf16 v[64:67], v[220:223], v[208:211], v[192:195]
	v_mfma_f32_16x16x32_bf16 v[36:39], v[174:177], v[204:207], v[36:39]
	v_mfma_f32_16x16x32_bf16 v[40:43], v[212:215], v[204:207], v[40:43]
	v_mfma_f32_16x16x32_bf16 v[44:47], v[154:157], v[204:207], v[44:47]
	v_mfma_f32_16x16x32_bf16 v[48:51], v[150:153], v[204:207], v[48:51]
	v_mfma_f32_16x16x32_bf16 v[64:67], v[150:153], v[158:161], v[64:67]
	s_movk_i32 s2, 0x100
	v_cmp_gt_u32_e32 vcc, s2, v3
	s_barrier
	s_and_saveexec_b64 s[2:3], vcc
	s_cbranch_execz .LBB0_911
	s_barrier

; #define LDA8(dst, b, h) _Pragma("unroll") for (int m = 0; m < 4; ++m) _Pragma("unroll") for (int k = 0; k < 2; ++k) \
;     dst[m][k] = *(const bf16x8*)((const char*)SA8(b, h) + lds_byte8(wr * 64 + m * 16 + fr, k * 32 + fq * 8))
; #define LDB8(dst, b, h) _Pragma("unroll") for (int n = 0; n < 2; ++n) _Pragma("unroll") for (int k = 0; k < 2; ++k) \
;     dst[n][k] = *(const bf16x8*)((const char*)SB8(b, h) + lds_byte8(wc * 32 + n * 16 + fr, k * 32 + fq * 8))
; #define WAIT_V8(n) asm volatile("s_waitcnt vmcnt(" #n ")" ::: "memory")
; #define WAIT_L8(n) asm volatile("s_waitcnt lgkmcnt(" #n ")" ::: "memory")
; #define BAR8 __builtin_amdgcn_s_barrier()
;     ...
;   { LDB8(B0, 0, 0); LDA8(At, 0, 0); STAGE8(SA8(1, 1), A, lda, brow + 128, nt - 1);
;     BAR8; WAIT_L8(0); MMA8(0, 0, At, B0); BAR8;
;     LDB8(B1, 0, 1); BAR8; WAIT_L8(0); MMA8(0, 1, At, B1); BAR8;
;     LDA8(At, 0, 1); WAIT_V8(4); BAR8; WAIT_L8(0); MMA8(1, 0, At, B0); MMA8(1, 1, At, B1); BAR8; }
.Lpk_exit_3:
	s_add_u32 s8, s8, 0x40780
	s_addc_u32 s9, s9, 0
	v_lshl_add_u64 v[132:133], s[8:9], 0, v[132:133]
	v_lshl_add_u64 v[0:1], v[0:1], 1, v[132:133]
	s_or_b32 m0, s100, 0xc000
	ds_read_b128 v[138:141], v171
	ds_read_b128 v[142:145], v171 offset:1024
	ds_read_b128 v[162:165], v171 offset:2048
	ds_read_b128 v[174:177], v171 offset:3072
	ds_read_b128 v[178:181], v156
	ds_read_b128 v[182:185], v156 offset:1024
	ds_read_b128 v[186:189], v155
	ds_read_b128 v[190:193], v155 offset:1024
	ds_read_b128 v[194:197], v154
	ds_read_b128 v[198:201], v154 offset:1024
	ds_read_b128 v[202:205], v153
	ds_read_b128 v[206:209], v153 offset:1024
	global_load_lds_dwordx4 v[0:1], off
	v_lshl_add_u64 v[0:1], s[8:9], 0, v[136:137]
	s_or_b32 m0, s100, 0xe000
	v_lshl_add_u64 v[0:1], v[134:135], 1, v[0:1]
	global_load_lds_dwordx4 v[0:1], off
	s_barrier
	s_waitcnt lgkmcnt(0)
	v_mfma_f32_16x16x32_bf16 v[128:131], v[178:181], v[138:141], v[128:131]
	v_mfma_f32_16x16x32_bf16 v[124:127], v[178:181], v[162:165], v[124:127]
	v_mfma_f32_16x16x32_bf16 v[120:123], v[186:189], v[138:141], v[120:123]
	v_mfma_f32_16x16x32_bf16 v[112:115], v[194:197], v[138:141], v[112:115]
	v_mfma_f32_16x16x32_bf16 v[128:131], v[182:185], v[142:145], v[128:131]
	v_mfma_f32_16x16x32_bf16 v[124:127], v[182:185], v[174:177], v[124:127]
	v_mfma_f32_16x16x32_bf16 v[120:123], v[190:193], v[142:145], v[120:123]
	v_mfma_f32_16x16x32_bf16 v[116:119], v[186:189], v[162:165], v[116:119]
	v_mfma_f32_16x16x32_bf16 v[112:115], v[198:201], v[142:145], v[112:115]
	v_mfma_f32_16x16x32_bf16 v[108:111], v[194:197], v[162:165], v[108:111]
	v_mfma_f32_16x16x32_bf16 v[104:107], v[202:205], v[138:141], v[104:107]
	v_mfma_f32_16x16x32_bf16 v[100:103], v[202:205], v[162:165], v[100:103]
	v_mfma_f32_16x16x32_bf16 v[132:135], v[190:193], v[174:177], v[116:119]
	v_mfma_f32_16x16x32_bf16 v[170:173], v[198:201], v[174:177], v[108:111]
	v_mfma_f32_16x16x32_bf16 v[210:213], v[206:209], v[142:145], v[104:107]
	v_mfma_f32_16x16x32_bf16 v[214:217], v[206:209], v[174:177], v[100:103]
	s_barrier
	s_nop 1
	ds_read_b128 v[100:103], v168
	ds_read_b128 v[104:107], v168 offset:1024
	ds_read_b128 v[108:111], v168 offset:2048
	ds_read_b128 v[116:119], v168 offset:3072
	s_barrier
	s_waitcnt lgkmcnt(0)
	v_mfma_f32_16x16x32_bf16 v[80:83], v[194:197], v[100:103], v[80:83]
	v_mfma_f32_16x16x32_bf16 v[76:79], v[194:197], v[108:111], v[76:79]
	v_mfma_f32_16x16x32_bf16 v[72:75], v[202:205], v[100:103], v[72:75]
	v_mfma_f32_16x16x32_bf16 v[68:71], v[202:205], v[108:111], v[68:71]
	v_mfma_f32_16x16x32_bf16 v[96:99], v[178:181], v[100:103], v[96:99]
	v_mfma_f32_16x16x32_bf16 v[92:95], v[178:181], v[108:111], v[92:95]
	v_mfma_f32_16x16x32_bf16 v[88:91], v[186:189], v[100:103], v[88:91]
	v_mfma_f32_16x16x32_bf16 v[84:87], v[186:189], v[108:111], v[84:87]
	v_mfma_f32_16x16x32_bf16 v[80:83], v[198:201], v[104:107], v[80:83]
	v_mfma_f32_16x16x32_bf16 v[76:79], v[198:201], v[116:119], v[76:79]
	v_mfma_f32_16x16x32_bf16 v[72:75], v[206:209], v[104:107], v[72:75]
	v_mfma_f32_16x16x32_bf16 v[68:71], v[206:209], v[116:119], v[68:71]
	v_mfma_f32_16x16x32_bf16 v[166:169], v[182:185], v[104:107], v[96:99]
	v_mfma_f32_16x16x32_bf16 v[178:181], v[182:185], v[116:119], v[92:95]
	v_mfma_f32_16x16x32_bf16 v[182:185], v[190:193], v[104:107], v[88:91]
	v_mfma_f32_16x16x32_bf16 v[186:189], v[190:193], v[116:119], v[84:87]
	s_barrier
	s_nop 0
	ds_read_b128 v[84:87], v156 offset:16384
	ds_read_b128 v[88:91], v156 offset:17408
	ds_read_b128 v[92:95], v155 offset:16384
	ds_read_b128 v[96:99], v155 offset:17408
	ds_read_b128 v[190:193], v154 offset:16384
	ds_read_b128 v[194:197], v154 offset:17408
	ds_read_b128 v[198:201], v153 offset:16384
	ds_read_b128 v[202:205], v153 offset:17408
	s_waitcnt vmcnt(4)
	s_barrier
	s_waitcnt lgkmcnt(0)
	v_mfma_f32_16x16x32_bf16 v[64:67], v[84:87], v[138:141], v[64:67]
	v_mfma_f32_16x16x32_bf16 v[60:63], v[84:87], v[162:165], v[60:63]
	v_mfma_f32_16x16x32_bf16 v[56:59], v[92:95], v[138:141], v[56:59]
	v_mfma_f32_16x16x32_bf16 v[52:55], v[92:95], v[162:165], v[52:55]
	v_mfma_f32_16x16x32_bf16 v[48:51], v[190:193], v[138:141], v[48:51]
	v_mfma_f32_16x16x32_bf16 v[44:47], v[190:193], v[162:165], v[44:47]
	v_mfma_f32_16x16x32_bf16 v[40:43], v[198:201], v[138:141], v[40:43]
	v_mfma_f32_16x16x32_bf16 v[36:39], v[198:201], v[162:165], v[36:39]
	v_mfma_f32_16x16x32_bf16 v[64:67], v[88:91], v[142:145], v[64:67]
	v_mfma_f32_16x16x32_bf16 v[60:63], v[88:91], v[174:177], v[60:63]
	v_mfma_f32_16x16x32_bf16 v[56:59], v[96:99], v[142:145], v[56:59]
	v_mfma_f32_16x16x32_bf16 v[52:55], v[96:99], v[174:177], v[52:55]
	v_mfma_f32_16x16x32_bf16 v[48:51], v[194:197], v[142:145], v[48:51]
	v_mfma_f32_16x16x32_bf16 v[44:47], v[194:197], v[174:177], v[44:47]
	v_mfma_f32_16x16x32_bf16 v[40:43], v[202:205], v[142:145], v[40:43]
	v_mfma_f32_16x16x32_bf16 v[36:39], v[202:205], v[174:177], v[36:39]
	v_mfma_f32_16x16x32_bf16 v[32:35], v[84:87], v[100:103], v[32:35]
	v_mfma_f32_16x16x32_bf16 v[28:31], v[84:87], v[108:111], v[28:31]
	v_mfma_f32_16x16x32_bf16 v[24:27], v[92:95], v[100:103], v[24:27]
	v_mfma_f32_16x16x32_bf16 v[20:23], v[92:95], v[108:111], v[20:23]
	v_mfma_f32_16x16x32_bf16 v[16:19], v[190:193], v[100:103], v[16:19]
	v_mfma_f32_16x16x32_bf16 v[12:15], v[190:193], v[108:111], v[12:15]
	v_mfma_f32_16x16x32_bf16 v[8:11], v[198:201], v[100:103], v[8:11]
	v_mfma_f32_16x16x32_bf16 v[4:7], v[198:201], v[108:111], v[4:7]
	v_mfma_f32_16x16x32_bf16 v[136:139], v[88:91], v[104:107], v[32:35]
	v_mfma_f32_16x16x32_bf16 v[140:143], v[88:91], v[116:119], v[28:31]
	v_mfma_f32_16x16x32_bf16 v[162:165], v[96:99], v[104:107], v[24:27]
	v_mfma_f32_16x16x32_bf16 v[174:177], v[96:99], v[116:119], v[20:23]
	v_mfma_f32_16x16x32_bf16 v[206:209], v[194:197], v[104:107], v[16:19]
	v_mfma_f32_16x16x32_bf16 v[190:193], v[194:197], v[116:119], v[12:15]
	v_mfma_f32_16x16x32_bf16 v[194:197], v[202:205], v[104:107], v[8:11]
	v_mfma_f32_16x16x32_bf16 v[198:201], v[202:205], v[116:119], v[4:7]
	s_barrier
; #define LDA8(dst, b, h) _Pragma("unroll") for (int m = 0; m < 4; ++m) _Pragma("unroll") for (int k = 0; k < 2; ++k) \
;     dst[m][k] = *(const bf16x8*)((const char*)SA8(b, h) + lds_byte8(wr * 64 + m * 16 + fr, k * 32 + fq * 8))
; #define LDB8(dst, b, h) _Pragma("unroll") for (int n = 0; n < 2; ++n) _Pragma("unroll") for (int k = 0; k < 2; ++k) \
;     dst[n][k] = *(const bf16x8*)((const char*)SB8(b, h) + lds_byte8(wc * 32 + n * 16 + fr, k * 32 + fq * 8))
; #define WAIT_V8(n) asm volatile("s_waitcnt vmcnt(" #n ")" ::: "memory")
; #define WAIT_L8(n) asm volatile("s_waitcnt lgkmcnt(" #n ")" ::: "memory")
; #define BAR8 __builtin_amdgcn_s_barrier()
;     ...
;   { LDB8(B0, 1, 0); LDA8(At, 1, 0); WAIT_V8(2); BAR8; WAIT_L8(0); MMA8(0, 0, At, B0); BAR8;
;     LDB8(B1, 1, 1); WAIT_V8(0); BAR8; WAIT_L8(0); MMA8(0, 1, At, B1); BAR8;
;     LDA8(At, 1, 1); BAR8; WAIT_L8(0); MMA8(1, 0, At, B0); MMA8(1, 1, At, B1); BAR8; }
;   if (wr == 0) BAR8;
;   __syncthreads();
	ds_read_b128 v[202:205], v161
	ds_read_b128 v[218:221], v161 offset:1024
	ds_read_b128 v[226:229], v161 offset:2048
	ds_read_b128 v[230:233], v161 offset:3072
	ds_read_b128 v[8:11], v156 offset:32768
	ds_read_b128 v[12:15], v156 offset:33792
	ds_read_b128 v[16:19], v155 offset:32768
	ds_read_b128 v[24:27], v155 offset:33792
	ds_read_b128 v[28:31], v154 offset:32768
	ds_read_b128 v[32:35], v154 offset:33792
	ds_read_b128 v[238:241], v153 offset:32768
	ds_read_b128 v[242:245], v153 offset:33792
	s_waitcnt vmcnt(2)
	s_barrier
	s_waitcnt lgkmcnt(0)
	v_mfma_f32_16x16x32_bf16 v[4:7], v[8:11], v[202:205], v[128:131]
	v_mfma_f32_16x16x32_bf16 v[104:107], v[12:15], v[218:221], v[4:7]
	v_mfma_f32_16x16x32_bf16 v[4:7], v[8:11], v[226:229], v[124:127]
	v_mfma_f32_16x16x32_bf16 v[116:119], v[12:15], v[230:233], v[4:7]
	v_mfma_f32_16x16x32_bf16 v[4:7], v[16:19], v[202:205], v[120:123]
	v_mfma_f32_16x16x32_bf16 v[100:103], v[24:27], v[218:221], v[4:7]
	v_mfma_f32_16x16x32_bf16 v[4:7], v[16:19], v[226:229], v[132:135]
	v_mfma_f32_16x16x32_bf16 v[108:111], v[24:27], v[230:233], v[4:7]
	v_mfma_f32_16x16x32_bf16 v[4:7], v[28:31], v[202:205], v[112:115]
	v_mfma_f32_16x16x32_bf16 v[92:95], v[32:35], v[218:221], v[4:7]
	v_mfma_f32_16x16x32_bf16 v[4:7], v[28:31], v[226:229], v[170:173]
	v_mfma_f32_16x16x32_bf16 v[96:99], v[32:35], v[230:233], v[4:7]
	v_mfma_f32_16x16x32_bf16 v[4:7], v[238:241], v[202:205], v[210:213]
	v_mfma_f32_16x16x32_bf16 v[84:87], v[242:245], v[218:221], v[4:7]
	v_mfma_f32_16x16x32_bf16 v[4:7], v[238:241], v[226:229], v[214:217]
	v_mfma_f32_16x16x32_bf16 v[88:91], v[242:245], v[230:233], v[4:7]
	s_barrier
	ds_read_b128 v[132:135], v158
	ds_read_b128 v[170:173], v158 offset:1024
	ds_read_b128 v[210:213], v158 offset:2048
	ds_read_b128 v[158:161], v158 offset:3072
	s_waitcnt vmcnt(0)
	s_barrier
	s_waitcnt lgkmcnt(0)
	v_mfma_f32_16x16x32_bf16 v[4:7], v[8:11], v[132:135], v[166:169]
	v_mfma_f32_16x16x32_bf16 v[8:11], v[8:11], v[210:213], v[178:181]
	v_mfma_f32_16x16x32_bf16 v[4:7], v[12:15], v[170:173], v[4:7]
	v_mfma_f32_16x16x32_bf16 v[20:23], v[12:15], v[158:161], v[8:11]
	v_mfma_f32_16x16x32_bf16 v[8:11], v[16:19], v[132:135], v[182:185]
	v_mfma_f32_16x16x32_bf16 v[12:15], v[16:19], v[210:213], v[186:189]
	v_mfma_f32_16x16x32_bf16 v[8:11], v[24:27], v[170:173], v[8:11]
	v_mfma_f32_16x16x32_bf16 v[24:27], v[24:27], v[158:161], v[12:15]
	v_mfma_f32_16x16x32_bf16 v[12:15], v[28:31], v[132:135], v[80:83]
	v_mfma_f32_16x16x32_bf16 v[16:19], v[28:31], v[210:213], v[76:79]
	v_mfma_f32_16x16x32_bf16 v[12:15], v[32:35], v[170:173], v[12:15]
	v_mfma_f32_16x16x32_bf16 v[28:31], v[32:35], v[158:161], v[16:19]
	v_mfma_f32_16x16x32_bf16 v[16:19], v[238:241], v[132:135], v[72:75]
	v_mfma_f32_16x16x32_bf16 v[32:35], v[238:241], v[210:213], v[68:71]
	v_mfma_f32_16x16x32_bf16 v[16:19], v[242:245], v[170:173], v[16:19]
	v_mfma_f32_16x16x32_bf16 v[32:35], v[242:245], v[158:161], v[32:35]
	s_barrier
	ds_read_b128 v[166:169], v156 offset:49152
	ds_read_b128 v[178:181], v156 offset:50176
	ds_read_b128 v[182:185], v155 offset:49152
	ds_read_b128 v[186:189], v155 offset:50176
	ds_read_b128 v[214:217], v154 offset:49152
	ds_read_b128 v[154:157], v154 offset:50176
	ds_read_b128 v[238:241], v153 offset:49152
	ds_read_b128 v[150:153], v153 offset:50176
	s_waitcnt lgkmcnt(0)
	v_mfma_f32_16x16x32_bf16 v[64:67], v[166:169], v[202:205], v[64:67]
	v_mfma_f32_16x16x32_bf16 v[60:63], v[166:169], v[226:229], v[60:63]
	v_mfma_f32_16x16x32_bf16 v[56:59], v[182:185], v[202:205], v[56:59]
	v_mfma_f32_16x16x32_bf16 v[52:55], v[182:185], v[226:229], v[52:55]
	v_mfma_f32_16x16x32_bf16 v[48:51], v[214:217], v[202:205], v[48:51]
	v_mfma_f32_16x16x32_bf16 v[44:47], v[214:217], v[226:229], v[44:47]
	v_mfma_f32_16x16x32_bf16 v[40:43], v[238:241], v[202:205], v[40:43]
	v_mfma_f32_16x16x32_bf16 v[36:39], v[238:241], v[226:229], v[36:39]
	v_mfma_f32_16x16x32_bf16 v[128:131], v[178:181], v[218:221], v[64:67]
	v_mfma_f32_16x16x32_bf16 v[124:127], v[178:181], v[230:233], v[60:63]
	v_mfma_f32_16x16x32_bf16 v[120:123], v[186:189], v[218:221], v[56:59]
	v_mfma_f32_16x16x32_bf16 v[112:115], v[186:189], v[230:233], v[52:55]
	v_mfma_f32_16x16x32_bf16 v[80:83], v[154:157], v[218:221], v[48:51]
	v_mfma_f32_16x16x32_bf16 v[76:79], v[154:157], v[230:233], v[44:47]
	v_mfma_f32_16x16x32_bf16 v[72:75], v[150:153], v[218:221], v[40:43]
	v_mfma_f32_16x16x32_bf16 v[68:71], v[150:153], v[230:233], v[36:39]
	v_mfma_f32_16x16x32_bf16 v[36:39], v[166:169], v[132:135], v[136:139]
	v_mfma_f32_16x16x32_bf16 v[64:67], v[178:181], v[170:173], v[36:39]
	v_mfma_f32_16x16x32_bf16 v[36:39], v[166:169], v[210:213], v[140:143]
	v_mfma_f32_16x16x32_bf16 v[60:63], v[178:181], v[158:161], v[36:39]
	v_mfma_f32_16x16x32_bf16 v[36:39], v[182:185], v[132:135], v[162:165]
	v_mfma_f32_16x16x32_bf16 v[56:59], v[186:189], v[170:173], v[36:39]
	v_mfma_f32_16x16x32_bf16 v[36:39], v[182:185], v[210:213], v[174:177]
	v_mfma_f32_16x16x32_bf16 v[52:55], v[186:189], v[158:161], v[36:39]
	v_mfma_f32_16x16x32_bf16 v[36:39], v[214:217], v[132:135], v[206:209]
	v_mfma_f32_16x16x32_bf16 v[48:51], v[154:157], v[170:173], v[36:39]
	v_mfma_f32_16x16x32_bf16 v[36:39], v[214:217], v[210:213], v[190:193]
	v_mfma_f32_16x16x32_bf16 v[44:47], v[154:157], v[158:161], v[36:39]
	v_mfma_f32_16x16x32_bf16 v[36:39], v[238:241], v[132:135], v[194:197]
	v_mfma_f32_16x16x32_bf16 v[40:43], v[150:153], v[170:173], v[36:39]
	v_mfma_f32_16x16x32_bf16 v[36:39], v[238:241], v[210:213], v[198:201]
	v_mfma_f32_16x16x32_bf16 v[36:39], v[150:153], v[158:161], v[36:39]
	s_movk_i32 s1, 0x100
	v_cmp_gt_u32_e32 vcc, s1, v3
	s_barrier
	s_and_saveexec_b64 s[8:9], vcc
	s_cbranch_execz .LBB0_1008
	s_barrier

; #define LDA8(dst, b, h) _Pragma("unroll") for (int m = 0; m < 4; ++m) _Pragma("unroll") for (int k = 0; k < 2; ++k) \
;     dst[m][k] = *(const bf16x8*)((const char*)SA8(b, h) + lds_byte8(wr * 64 + m * 16 + fr, k * 32 + fq * 8))
; #define LDB8(dst, b, h) _Pragma("unroll") for (int n = 0; n < 2; ++n) _Pragma("unroll") for (int k = 0; k < 2; ++k) \
;     dst[n][k] = *(const bf16x8*)((const char*)SB8(b, h) + lds_byte8(wc * 32 + n * 16 + fr, k * 32 + fq * 8))
; #define WAIT_V8(n) asm volatile("s_waitcnt vmcnt(" #n ")" ::: "memory")
; #define WAIT_L8(n) asm volatile("s_waitcnt lgkmcnt(" #n ")" ::: "memory")
; #define BAR8 __builtin_amdgcn_s_barrier()
;     ...
;   { LDB8(B0, 0, 0); LDA8(At, 0, 0); STAGE8(SA8(1, 1), A, lda, brow + 128, nt - 1);
;     BAR8; WAIT_L8(0); MMA8(0, 0, At, B0); BAR8;
;     LDB8(B1, 0, 1); BAR8; WAIT_L8(0); MMA8(0, 1, At, B1); BAR8;
;     LDA8(At, 0, 1); WAIT_V8(4); BAR8; WAIT_L8(0); MMA8(1, 0, At, B0); MMA8(1, 1, At, B1); BAR8; }
.Lpk_exit_4:
	s_add_u32 s8, s8, 0x40780
	s_addc_u32 s9, s9, 0
	v_lshl_add_u64 v[132:133], s[8:9], 0, v[132:133]
	v_lshl_add_u64 v[0:1], v[0:1], 1, v[132:133]
	s_or_b32 m0, s100, 0xc000
	ds_read_b128 v[138:141], v171
	ds_read_b128 v[142:145], v171 offset:1024
	ds_read_b128 v[162:165], v171 offset:2048
	ds_read_b128 v[174:177], v171 offset:3072
	ds_read_b128 v[178:181], v156
	ds_read_b128 v[182:185], v156 offset:1024
	ds_read_b128 v[186:189], v155
	ds_read_b128 v[190:193], v155 offset:1024
	ds_read_b128 v[194:197], v154
	ds_read_b128 v[198:201], v154 offset:1024
	ds_read_b128 v[202:205], v153
	ds_read_b128 v[206:209], v153 offset:1024
	global_load_lds_dwordx4 v[0:1], off
	v_lshl_add_u64 v[0:1], s[8:9], 0, v[136:137]
	s_or_b32 m0, s100, 0xe000
	v_lshl_add_u64 v[0:1], v[134:135], 1, v[0:1]
	global_load_lds_dwordx4 v[0:1], off
	s_barrier
	s_waitcnt lgkmcnt(0)
	v_mfma_f32_16x16x32_f16 v[128:131], v[178:181], v[138:141], v[128:131]
	v_mfma_f32_16x16x32_f16 v[124:127], v[178:181], v[162:165], v[124:127]
	v_mfma_f32_16x16x32_f16 v[120:123], v[186:189], v[138:141], v[120:123]
	v_mfma_f32_16x16x32_f16 v[112:115], v[194:197], v[138:141], v[112:115]
	v_mfma_f32_16x16x32_f16 v[128:131], v[182:185], v[142:145], v[128:131]
	v_mfma_f32_16x16x32_f16 v[124:127], v[182:185], v[174:177], v[124:127]
	v_mfma_f32_16x16x32_f16 v[120:123], v[190:193], v[142:145], v[120:123]
	v_mfma_f32_16x16x32_f16 v[116:119], v[186:189], v[162:165], v[116:119]
	v_mfma_f32_16x16x32_f16 v[112:115], v[198:201], v[142:145], v[112:115]
	v_mfma_f32_16x16x32_f16 v[108:111], v[194:197], v[162:165], v[108:111]
	v_mfma_f32_16x16x32_f16 v[104:107], v[202:205], v[138:141], v[104:107]
	v_mfma_f32_16x16x32_f16 v[100:103], v[202:205], v[162:165], v[100:103]
	v_mfma_f32_16x16x32_f16 v[132:135], v[190:193], v[174:177], v[116:119]
	v_mfma_f32_16x16x32_f16 v[170:173], v[198:201], v[174:177], v[108:111]
	v_mfma_f32_16x16x32_f16 v[210:213], v[206:209], v[142:145], v[104:107]
	v_mfma_f32_16x16x32_f16 v[214:217], v[206:209], v[174:177], v[100:103]
	s_barrier
	s_nop 1
	ds_read_b128 v[100:103], v168
	ds_read_b128 v[104:107], v168 offset:1024
	ds_read_b128 v[108:111], v168 offset:2048
	ds_read_b128 v[116:119], v168 offset:3072
	s_barrier
	s_waitcnt lgkmcnt(0)
	v_mfma_f32_16x16x32_f16 v[80:83], v[194:197], v[100:103], v[80:83]
	v_mfma_f32_16x16x32_f16 v[76:79], v[194:197], v[108:111], v[76:79]
	v_mfma_f32_16x16x32_f16 v[72:75], v[202:205], v[100:103], v[72:75]
	v_mfma_f32_16x16x32_f16 v[68:71], v[202:205], v[108:111], v[68:71]
	v_mfma_f32_16x16x32_f16 v[96:99], v[178:181], v[100:103], v[96:99]
	v_mfma_f32_16x16x32_f16 v[92:95], v[178:181], v[108:111], v[92:95]
	v_mfma_f32_16x16x32_f16 v[88:91], v[186:189], v[100:103], v[88:91]
	v_mfma_f32_16x16x32_f16 v[84:87], v[186:189], v[108:111], v[84:87]
	v_mfma_f32_16x16x32_f16 v[80:83], v[198:201], v[104:107], v[80:83]
	v_mfma_f32_16x16x32_f16 v[76:79], v[198:201], v[116:119], v[76:79]
	v_mfma_f32_16x16x32_f16 v[72:75], v[206:209], v[104:107], v[72:75]
	v_mfma_f32_16x16x32_f16 v[68:71], v[206:209], v[116:119], v[68:71]
	v_mfma_f32_16x16x32_f16 v[166:169], v[182:185], v[104:107], v[96:99]
	v_mfma_f32_16x16x32_f16 v[178:181], v[182:185], v[116:119], v[92:95]
	v_mfma_f32_16x16x32_f16 v[182:185], v[190:193], v[104:107], v[88:91]
	v_mfma_f32_16x16x32_f16 v[186:189], v[190:193], v[116:119], v[84:87]
	s_barrier
	s_nop 0
	ds_read_b128 v[84:87], v156 offset:16384
	ds_read_b128 v[88:91], v156 offset:17408
	ds_read_b128 v[92:95], v155 offset:16384
	ds_read_b128 v[96:99], v155 offset:17408
	ds_read_b128 v[190:193], v154 offset:16384
	ds_read_b128 v[194:197], v154 offset:17408
	ds_read_b128 v[198:201], v153 offset:16384
	ds_read_b128 v[202:205], v153 offset:17408
	s_waitcnt vmcnt(4)
	s_barrier
	s_waitcnt lgkmcnt(0)
	v_mfma_f32_16x16x32_f16 v[64:67], v[84:87], v[138:141], v[64:67]
	v_mfma_f32_16x16x32_f16 v[60:63], v[84:87], v[162:165], v[60:63]
	v_mfma_f32_16x16x32_f16 v[56:59], v[92:95], v[138:141], v[56:59]
	v_mfma_f32_16x16x32_f16 v[52:55], v[92:95], v[162:165], v[52:55]
	v_mfma_f32_16x16x32_f16 v[48:51], v[190:193], v[138:141], v[48:51]
	v_mfma_f32_16x16x32_f16 v[44:47], v[190:193], v[162:165], v[44:47]
	v_mfma_f32_16x16x32_f16 v[40:43], v[198:201], v[138:141], v[40:43]
	v_mfma_f32_16x16x32_f16 v[36:39], v[198:201], v[162:165], v[36:39]
	v_mfma_f32_16x16x32_f16 v[64:67], v[88:91], v[142:145], v[64:67]
	v_mfma_f32_16x16x32_f16 v[60:63], v[88:91], v[174:177], v[60:63]
	v_mfma_f32_16x16x32_f16 v[56:59], v[96:99], v[142:145], v[56:59]
	v_mfma_f32_16x16x32_f16 v[52:55], v[96:99], v[174:177], v[52:55]
	v_mfma_f32_16x16x32_f16 v[48:51], v[194:197], v[142:145], v[48:51]
	v_mfma_f32_16x16x32_f16 v[44:47], v[194:197], v[174:177], v[44:47]
	v_mfma_f32_16x16x32_f16 v[40:43], v[202:205], v[142:145], v[40:43]
	v_mfma_f32_16x16x32_f16 v[36:39], v[202:205], v[174:177], v[36:39]
	v_mfma_f32_16x16x32_f16 v[32:35], v[84:87], v[100:103], v[32:35]
	v_mfma_f32_16x16x32_f16 v[28:31], v[84:87], v[108:111], v[28:31]
	v_mfma_f32_16x16x32_f16 v[24:27], v[92:95], v[100:103], v[24:27]
	v_mfma_f32_16x16x32_f16 v[20:23], v[92:95], v[108:111], v[20:23]
	v_mfma_f32_16x16x32_f16 v[16:19], v[190:193], v[100:103], v[16:19]
	v_mfma_f32_16x16x32_f16 v[12:15], v[190:193], v[108:111], v[12:15]
	v_mfma_f32_16x16x32_f16 v[8:11], v[198:201], v[100:103], v[8:11]
	v_mfma_f32_16x16x32_f16 v[4:7], v[198:201], v[108:111], v[4:7]
	v_mfma_f32_16x16x32_f16 v[136:139], v[88:91], v[104:107], v[32:35]
	v_mfma_f32_16x16x32_f16 v[140:143], v[88:91], v[116:119], v[28:31]
	v_mfma_f32_16x16x32_f16 v[162:165], v[96:99], v[104:107], v[24:27]
	v_mfma_f32_16x16x32_f16 v[174:177], v[96:99], v[116:119], v[20:23]
	v_mfma_f32_16x16x32_f16 v[206:209], v[194:197], v[104:107], v[16:19]
	v_mfma_f32_16x16x32_f16 v[190:193], v[194:197], v[116:119], v[12:15]
	v_mfma_f32_16x16x32_f16 v[194:197], v[202:205], v[104:107], v[8:11]
	v_mfma_f32_16x16x32_f16 v[198:201], v[202:205], v[116:119], v[4:7]
	s_barrier
; #define LDA8(dst, b, h) _Pragma("unroll") for (int m = 0; m < 4; ++m) _Pragma("unroll") for (int k = 0; k < 2; ++k) \
;     dst[m][k] = *(const bf16x8*)((const char*)SA8(b, h) + lds_byte8(wr * 64 + m * 16 + fr, k * 32 + fq * 8))
; #define LDB8(dst, b, h) _Pragma("unroll") for (int n = 0; n < 2; ++n) _Pragma("unroll") for (int k = 0; k < 2; ++k) \
;     dst[n][k] = *(const bf16x8*)((const char*)SB8(b, h) + lds_byte8(wc * 32 + n * 16 + fr, k * 32 + fq * 8))
; #define WAIT_V8(n) asm volatile("s_waitcnt vmcnt(" #n ")" ::: "memory")
; #define WAIT_L8(n) asm volatile("s_waitcnt lgkmcnt(" #n ")" ::: "memory")
; #define BAR8 __builtin_amdgcn_s_barrier()
;     ...
;   { LDB8(B0, 1, 0); LDA8(At, 1, 0); WAIT_V8(2); BAR8; WAIT_L8(0); MMA8(0, 0, At, B0); BAR8;
;     LDB8(B1, 1, 1); WAIT_V8(0); BAR8; WAIT_L8(0); MMA8(0, 1, At, B1); BAR8;
;     LDA8(At, 1, 1); BAR8; WAIT_L8(0); MMA8(1, 0, At, B0); MMA8(1, 1, At, B1); BAR8; }
;   if (wr == 0) BAR8;
;   __syncthreads();
	ds_read_b128 v[202:205], v161
	ds_read_b128 v[218:221], v161 offset:1024
	ds_read_b128 v[226:229], v161 offset:2048
	ds_read_b128 v[230:233], v161 offset:3072
	ds_read_b128 v[8:11], v156 offset:32768
	ds_read_b128 v[12:15], v156 offset:33792
	ds_read_b128 v[16:19], v155 offset:32768
	ds_read_b128 v[24:27], v155 offset:33792
	ds_read_b128 v[28:31], v154 offset:32768
	ds_read_b128 v[32:35], v154 offset:33792
	ds_read_b128 v[238:241], v153 offset:32768
	ds_read_b128 v[242:245], v153 offset:33792
	s_waitcnt vmcnt(2)
	s_barrier
	s_waitcnt lgkmcnt(0)
	v_mfma_f32_16x16x32_f16 v[4:7], v[8:11], v[202:205], v[128:131]
	v_mfma_f32_16x16x32_f16 v[104:107], v[12:15], v[218:221], v[4:7]
	v_mfma_f32_16x16x32_f16 v[4:7], v[8:11], v[226:229], v[124:127]
	v_mfma_f32_16x16x32_f16 v[116:119], v[12:15], v[230:233], v[4:7]
	v_mfma_f32_16x16x32_f16 v[4:7], v[16:19], v[202:205], v[120:123]
	v_mfma_f32_16x16x32_f16 v[100:103], v[24:27], v[218:221], v[4:7]
	v_mfma_f32_16x16x32_f16 v[4:7], v[16:19], v[226:229], v[132:135]
	v_mfma_f32_16x16x32_f16 v[108:111], v[24:27], v[230:233], v[4:7]
	v_mfma_f32_16x16x32_f16 v[4:7], v[28:31], v[202:205], v[112:115]
	v_mfma_f32_16x16x32_f16 v[92:95], v[32:35], v[218:221], v[4:7]
	v_mfma_f32_16x16x32_f16 v[4:7], v[28:31], v[226:229], v[170:173]
	v_mfma_f32_16x16x32_f16 v[96:99], v[32:35], v[230:233], v[4:7]
	v_mfma_f32_16x16x32_f16 v[4:7], v[238:241], v[202:205], v[210:213]
	v_mfma_f32_16x16x32_f16 v[84:87], v[242:245], v[218:221], v[4:7]
	v_mfma_f32_16x16x32_f16 v[4:7], v[238:241], v[226:229], v[214:217]
	v_mfma_f32_16x16x32_f16 v[88:91], v[242:245], v[230:233], v[4:7]
	s_barrier
	ds_read_b128 v[132:135], v158
	ds_read_b128 v[170:173], v158 offset:1024
	ds_read_b128 v[210:213], v158 offset:2048
	ds_read_b128 v[158:161], v158 offset:3072
	s_waitcnt vmcnt(0)
	s_barrier
	s_waitcnt lgkmcnt(0)
	v_mfma_f32_16x16x32_f16 v[4:7], v[8:11], v[132:135], v[166:169]
	v_mfma_f32_16x16x32_f16 v[8:11], v[8:11], v[210:213], v[178:181]
	v_mfma_f32_16x16x32_f16 v[4:7], v[12:15], v[170:173], v[4:7]
	v_mfma_f32_16x16x32_f16 v[20:23], v[12:15], v[158:161], v[8:11]
	v_mfma_f32_16x16x32_f16 v[8:11], v[16:19], v[132:135], v[182:185]
	v_mfma_f32_16x16x32_f16 v[12:15], v[16:19], v[210:213], v[186:189]
	v_mfma_f32_16x16x32_f16 v[8:11], v[24:27], v[170:173], v[8:11]
	v_mfma_f32_16x16x32_f16 v[24:27], v[24:27], v[158:161], v[12:15]
	v_mfma_f32_16x16x32_f16 v[12:15], v[28:31], v[132:135], v[80:83]
	v_mfma_f32_16x16x32_f16 v[16:19], v[28:31], v[210:213], v[76:79]
	v_mfma_f32_16x16x32_f16 v[12:15], v[32:35], v[170:173], v[12:15]
	v_mfma_f32_16x16x32_f16 v[28:31], v[32:35], v[158:161], v[16:19]
	v_mfma_f32_16x16x32_f16 v[16:19], v[238:241], v[132:135], v[72:75]
	v_mfma_f32_16x16x32_f16 v[32:35], v[238:241], v[210:213], v[68:71]
	v_mfma_f32_16x16x32_f16 v[16:19], v[242:245], v[170:173], v[16:19]
	v_mfma_f32_16x16x32_f16 v[32:35], v[242:245], v[158:161], v[32:35]
	s_barrier
	ds_read_b128 v[166:169], v156 offset:49152
	ds_read_b128 v[178:181], v156 offset:50176
	ds_read_b128 v[182:185], v155 offset:49152
	ds_read_b128 v[186:189], v155 offset:50176
	ds_read_b128 v[214:217], v154 offset:49152
	ds_read_b128 v[154:157], v154 offset:50176
	ds_read_b128 v[238:241], v153 offset:49152
	ds_read_b128 v[150:153], v153 offset:50176
	s_waitcnt lgkmcnt(0)
	v_mfma_f32_16x16x32_f16 v[64:67], v[166:169], v[202:205], v[64:67]
	v_mfma_f32_16x16x32_f16 v[60:63], v[166:169], v[226:229], v[60:63]
	v_mfma_f32_16x16x32_f16 v[56:59], v[182:185], v[202:205], v[56:59]
	v_mfma_f32_16x16x32_f16 v[52:55], v[182:185], v[226:229], v[52:55]
	v_mfma_f32_16x16x32_f16 v[48:51], v[214:217], v[202:205], v[48:51]
	v_mfma_f32_16x16x32_f16 v[44:47], v[214:217], v[226:229], v[44:47]
	v_mfma_f32_16x16x32_f16 v[40:43], v[238:241], v[202:205], v[40:43]
	v_mfma_f32_16x16x32_f16 v[36:39], v[238:241], v[226:229], v[36:39]
	v_mfma_f32_16x16x32_f16 v[128:131], v[178:181], v[218:221], v[64:67]
	v_mfma_f32_16x16x32_f16 v[124:127], v[178:181], v[230:233], v[60:63]
	v_mfma_f32_16x16x32_f16 v[120:123], v[186:189], v[218:221], v[56:59]
	v_mfma_f32_16x16x32_f16 v[112:115], v[186:189], v[230:233], v[52:55]
	v_mfma_f32_16x16x32_f16 v[80:83], v[154:157], v[218:221], v[48:51]
	v_mfma_f32_16x16x32_f16 v[76:79], v[154:157], v[230:233], v[44:47]
	v_mfma_f32_16x16x32_f16 v[72:75], v[150:153], v[218:221], v[40:43]
	v_mfma_f32_16x16x32_f16 v[68:71], v[150:153], v[230:233], v[36:39]
	v_mfma_f32_16x16x32_f16 v[36:39], v[166:169], v[132:135], v[136:139]
	v_mfma_f32_16x16x32_f16 v[64:67], v[178:181], v[170:173], v[36:39]
	v_mfma_f32_16x16x32_f16 v[36:39], v[166:169], v[210:213], v[140:143]
	v_mfma_f32_16x16x32_f16 v[60:63], v[178:181], v[158:161], v[36:39]
	v_mfma_f32_16x16x32_f16 v[36:39], v[182:185], v[132:135], v[162:165]
	v_mfma_f32_16x16x32_f16 v[56:59], v[186:189], v[170:173], v[36:39]
	v_mfma_f32_16x16x32_f16 v[36:39], v[182:185], v[210:213], v[174:177]
	v_mfma_f32_16x16x32_f16 v[52:55], v[186:189], v[158:161], v[36:39]
	v_mfma_f32_16x16x32_f16 v[36:39], v[214:217], v[132:135], v[206:209]
	v_mfma_f32_16x16x32_f16 v[48:51], v[154:157], v[170:173], v[36:39]
	v_mfma_f32_16x16x32_f16 v[36:39], v[214:217], v[210:213], v[190:193]
	v_mfma_f32_16x16x32_f16 v[44:47], v[154:157], v[158:161], v[36:39]
	v_mfma_f32_16x16x32_f16 v[36:39], v[238:241], v[132:135], v[194:197]
	v_mfma_f32_16x16x32_f16 v[40:43], v[150:153], v[170:173], v[36:39]
	v_mfma_f32_16x16x32_f16 v[36:39], v[238:241], v[210:213], v[198:201]
	v_mfma_f32_16x16x32_f16 v[36:39], v[150:153], v[158:161], v[36:39]
	s_movk_i32 s8, 0x100
	v_cmp_gt_u32_e32 vcc, s8, v3
	s_barrier
	s_and_saveexec_b64 s[8:9], vcc
	s_cbranch_execz .LBB0_1018
	s_barrier

; #define LDA8(dst, b, h) _Pragma("unroll") for (int m = 0; m < 4; ++m) _Pragma("unroll") for (int k = 0; k < 2; ++k) \
;     dst[m][k] = *(const bf16x8*)((const char*)SA8(b, h) + lds_byte8(wr * 64 + m * 16 + fr, k * 32 + fq * 8))
; #define LDB8(dst, b, h) _Pragma("unroll") for (int n = 0; n < 2; ++n) _Pragma("unroll") for (int k = 0; k < 2; ++k) \
;     dst[n][k] = *(const bf16x8*)((const char*)SB8(b, h) + lds_byte8(wc * 32 + n * 16 + fr, k * 32 + fq * 8))
; #define WAIT_V8(n) asm volatile("s_waitcnt vmcnt(" #n ")" ::: "memory")
; #define WAIT_L8(n) asm volatile("s_waitcnt lgkmcnt(" #n ")" ::: "memory")
; #define BAR8 __builtin_amdgcn_s_barrier()
;     ...
;   { LDB8(B0, 0, 0); LDA8(At, 0, 0); STAGE8(SA8(1, 1), A, lda, brow + 128, nt - 1);
;     BAR8; WAIT_L8(0); MMA8(0, 0, At, B0); BAR8;
;     LDB8(B1, 0, 1); BAR8; WAIT_L8(0); MMA8(0, 1, At, B1); BAR8;
;     LDA8(At, 0, 1); WAIT_V8(4); BAR8; WAIT_L8(0); MMA8(1, 0, At, B0); MMA8(1, 1, At, B1); BAR8; }
.Lpk_exit_5:
	s_add_u32 s2, s2, s27
	s_addc_u32 s3, s3, 0
	s_add_u32 s2, s2, 0x3000380
	s_addc_u32 s3, s3, 0
	v_lshl_add_u64 v[136:137], v[136:137], 1, s[2:3]
	v_lshl_add_u64 v[0:1], v[0:1], 1, v[136:137]
	s_or_b32 m0, s100, 0xc000
	ds_read_b128 v[138:141], v171
	ds_read_b128 v[142:145], v171 offset:1024
	ds_read_b128 v[162:165], v171 offset:2048
	ds_read_b128 v[168:171], v171 offset:3072
	ds_read_b128 v[174:177], v156
	ds_read_b128 v[178:181], v156 offset:1024
	ds_read_b128 v[182:185], v155
	ds_read_b128 v[186:189], v155 offset:1024
	ds_read_b128 v[190:193], v154
	ds_read_b128 v[194:197], v154 offset:1024
	ds_read_b128 v[198:201], v153
	ds_read_b128 v[202:205], v153 offset:1024
	global_load_lds_dwordx4 v[0:1], off
	v_lshl_add_u64 v[0:1], v[134:135], 1, s[2:3]
	s_or_b32 m0, s100, 0xe000
	v_lshl_add_u64 v[0:1], v[132:133], 1, v[0:1]
	global_load_lds_dwordx4 v[0:1], off
	s_barrier
	s_waitcnt lgkmcnt(0)
	v_mfma_f32_16x16x32_bf16 v[128:131], v[174:177], v[138:141], v[128:131]
	v_mfma_f32_16x16x32_bf16 v[124:127], v[174:177], v[162:165], v[124:127]
	v_mfma_f32_16x16x32_bf16 v[120:123], v[182:185], v[138:141], v[120:123]
	v_mfma_f32_16x16x32_bf16 v[112:115], v[190:193], v[138:141], v[112:115]
	v_mfma_f32_16x16x32_bf16 v[128:131], v[178:181], v[142:145], v[128:131]
	v_mfma_f32_16x16x32_bf16 v[124:127], v[178:181], v[168:171], v[124:127]
	v_mfma_f32_16x16x32_bf16 v[120:123], v[186:189], v[142:145], v[120:123]
	v_mfma_f32_16x16x32_bf16 v[116:119], v[182:185], v[162:165], v[116:119]
	v_mfma_f32_16x16x32_bf16 v[112:115], v[194:197], v[142:145], v[112:115]
	v_mfma_f32_16x16x32_bf16 v[108:111], v[190:193], v[162:165], v[108:111]
	v_mfma_f32_16x16x32_bf16 v[104:107], v[198:201], v[138:141], v[104:107]
	v_mfma_f32_16x16x32_bf16 v[100:103], v[198:201], v[162:165], v[100:103]
	v_mfma_f32_16x16x32_bf16 v[132:135], v[186:189], v[168:171], v[116:119]
	v_mfma_f32_16x16x32_bf16 v[206:209], v[194:197], v[168:171], v[108:111]
	v_mfma_f32_16x16x32_bf16 v[210:213], v[202:205], v[142:145], v[104:107]
	v_mfma_f32_16x16x32_bf16 v[214:217], v[202:205], v[168:171], v[100:103]
	s_barrier
	s_nop 1
	ds_read_b128 v[100:103], v167
	ds_read_b128 v[104:107], v167 offset:1024
	ds_read_b128 v[108:111], v167 offset:2048
	ds_read_b128 v[116:119], v167 offset:3072
	s_barrier
	s_waitcnt lgkmcnt(0)
	v_mfma_f32_16x16x32_bf16 v[80:83], v[190:193], v[100:103], v[80:83]
	v_mfma_f32_16x16x32_bf16 v[76:79], v[190:193], v[108:111], v[76:79]
	v_mfma_f32_16x16x32_bf16 v[72:75], v[198:201], v[100:103], v[72:75]
	v_mfma_f32_16x16x32_bf16 v[68:71], v[198:201], v[108:111], v[68:71]
	v_mfma_f32_16x16x32_bf16 v[96:99], v[174:177], v[100:103], v[96:99]
	v_mfma_f32_16x16x32_bf16 v[92:95], v[174:177], v[108:111], v[92:95]
	v_mfma_f32_16x16x32_bf16 v[88:91], v[182:185], v[100:103], v[88:91]
	v_mfma_f32_16x16x32_bf16 v[84:87], v[182:185], v[108:111], v[84:87]
	v_mfma_f32_16x16x32_bf16 v[80:83], v[194:197], v[104:107], v[80:83]
	v_mfma_f32_16x16x32_bf16 v[76:79], v[194:197], v[116:119], v[76:79]
	v_mfma_f32_16x16x32_bf16 v[72:75], v[202:205], v[104:107], v[72:75]
	v_mfma_f32_16x16x32_bf16 v[68:71], v[202:205], v[116:119], v[68:71]
	v_mfma_f32_16x16x32_bf16 v[218:221], v[178:181], v[104:107], v[96:99]
	v_mfma_f32_16x16x32_bf16 v[172:175], v[178:181], v[116:119], v[92:95]
	v_mfma_f32_16x16x32_bf16 v[176:179], v[186:189], v[104:107], v[88:91]
	v_mfma_f32_16x16x32_bf16 v[180:183], v[186:189], v[116:119], v[84:87]
	s_barrier
	s_nop 0
	ds_read_b128 v[84:87], v156 offset:16384
	ds_read_b128 v[88:91], v156 offset:17408
	ds_read_b128 v[92:95], v155 offset:16384
	ds_read_b128 v[96:99], v155 offset:17408
	ds_read_b128 v[184:187], v154 offset:16384
	ds_read_b128 v[188:191], v154 offset:17408
	ds_read_b128 v[192:195], v153 offset:16384
	ds_read_b128 v[196:199], v153 offset:17408
	s_waitcnt vmcnt(4)
	s_barrier
	s_waitcnt lgkmcnt(0)
	v_mfma_f32_16x16x32_bf16 v[64:67], v[84:87], v[138:141], v[64:67]
	v_mfma_f32_16x16x32_bf16 v[60:63], v[84:87], v[162:165], v[60:63]
	v_mfma_f32_16x16x32_bf16 v[56:59], v[92:95], v[138:141], v[56:59]
	v_mfma_f32_16x16x32_bf16 v[52:55], v[92:95], v[162:165], v[52:55]
	v_mfma_f32_16x16x32_bf16 v[48:51], v[184:187], v[138:141], v[48:51]
	v_mfma_f32_16x16x32_bf16 v[44:47], v[184:187], v[162:165], v[44:47]
	v_mfma_f32_16x16x32_bf16 v[40:43], v[192:195], v[138:141], v[40:43]
	v_mfma_f32_16x16x32_bf16 v[36:39], v[192:195], v[162:165], v[36:39]
	v_mfma_f32_16x16x32_bf16 v[64:67], v[88:91], v[142:145], v[64:67]
	v_mfma_f32_16x16x32_bf16 v[60:63], v[88:91], v[168:171], v[60:63]
	v_mfma_f32_16x16x32_bf16 v[56:59], v[96:99], v[142:145], v[56:59]
	v_mfma_f32_16x16x32_bf16 v[52:55], v[96:99], v[168:171], v[52:55]
	v_mfma_f32_16x16x32_bf16 v[48:51], v[188:191], v[142:145], v[48:51]
	v_mfma_f32_16x16x32_bf16 v[44:47], v[188:191], v[168:171], v[44:47]
	v_mfma_f32_16x16x32_bf16 v[40:43], v[196:199], v[142:145], v[40:43]
	v_mfma_f32_16x16x32_bf16 v[36:39], v[196:199], v[168:171], v[36:39]
	v_mfma_f32_16x16x32_bf16 v[32:35], v[84:87], v[100:103], v[32:35]
	v_mfma_f32_16x16x32_bf16 v[28:31], v[84:87], v[108:111], v[28:31]
	v_mfma_f32_16x16x32_bf16 v[24:27], v[92:95], v[100:103], v[24:27]
	v_mfma_f32_16x16x32_bf16 v[20:23], v[92:95], v[108:111], v[20:23]
	v_mfma_f32_16x16x32_bf16 v[16:19], v[184:187], v[100:103], v[16:19]
	v_mfma_f32_16x16x32_bf16 v[12:15], v[184:187], v[108:111], v[12:15]
	v_mfma_f32_16x16x32_bf16 v[8:11], v[192:195], v[100:103], v[8:11]
	v_mfma_f32_16x16x32_bf16 v[4:7], v[192:195], v[108:111], v[4:7]
	v_mfma_f32_16x16x32_bf16 v[136:139], v[88:91], v[104:107], v[32:35]
	v_mfma_f32_16x16x32_bf16 v[140:143], v[88:91], v[116:119], v[28:31]
	v_mfma_f32_16x16x32_bf16 v[162:165], v[96:99], v[104:107], v[24:27]
	v_mfma_f32_16x16x32_bf16 v[166:169], v[96:99], v[116:119], v[20:23]
	v_mfma_f32_16x16x32_bf16 v[200:203], v[188:191], v[104:107], v[16:19]
	v_mfma_f32_16x16x32_bf16 v[184:187], v[188:191], v[116:119], v[12:15]
	v_mfma_f32_16x16x32_bf16 v[188:191], v[196:199], v[104:107], v[8:11]
	v_mfma_f32_16x16x32_bf16 v[192:195], v[196:199], v[116:119], v[4:7]
	s_barrier
; #define LDA8(dst, b, h) _Pragma("unroll") for (int m = 0; m < 4; ++m) _Pragma("unroll") for (int k = 0; k < 2; ++k) \
;     dst[m][k] = *(const bf16x8*)((const char*)SA8(b, h) + lds_byte8(wr * 64 + m * 16 + fr, k * 32 + fq * 8))
; #define LDB8(dst, b, h) _Pragma("unroll") for (int n = 0; n < 2; ++n) _Pragma("unroll") for (int k = 0; k < 2; ++k) \
;     dst[n][k] = *(const bf16x8*)((const char*)SB8(b, h) + lds_byte8(wc * 32 + n * 16 + fr, k * 32 + fq * 8))
; #define WAIT_V8(n) asm volatile("s_waitcnt vmcnt(" #n ")" ::: "memory")
; #define WAIT_L8(n) asm volatile("s_waitcnt lgkmcnt(" #n ")" ::: "memory")
; #define BAR8 __builtin_amdgcn_s_barrier()
;     ...
;   { LDB8(B0, 1, 0); LDA8(At, 1, 0); WAIT_V8(2); BAR8; WAIT_L8(0); MMA8(0, 0, At, B0); BAR8;
;     LDB8(B1, 1, 1); WAIT_V8(0); BAR8; WAIT_L8(0); MMA8(0, 1, At, B1); BAR8;
;     LDA8(At, 1, 1); BAR8; WAIT_L8(0); MMA8(1, 0, At, B0); MMA8(1, 1, At, B1); BAR8; }
;   if (wr == 0) BAR8;
;   __syncthreads();
	ds_read_b128 v[196:199], v160
	ds_read_b128 v[226:229], v160 offset:1024
	ds_read_b128 v[230:233], v160 offset:2048
	ds_read_b128 v[238:241], v160 offset:3072
	ds_read_b128 v[8:11], v156 offset:32768
	ds_read_b128 v[12:15], v156 offset:33792
	ds_read_b128 v[16:19], v155 offset:32768
	ds_read_b128 v[24:27], v155 offset:33792
	ds_read_b128 v[28:31], v154 offset:32768
	ds_read_b128 v[32:35], v154 offset:33792
	ds_read_b128 v[242:245], v153 offset:32768
	ds_read_b128 v[246:249], v153 offset:33792
	s_waitcnt vmcnt(2)
	s_barrier
	s_waitcnt lgkmcnt(0)
	v_mfma_f32_16x16x32_bf16 v[4:7], v[8:11], v[196:199], v[128:131]
	v_mfma_f32_16x16x32_bf16 v[104:107], v[12:15], v[226:229], v[4:7]
	v_mfma_f32_16x16x32_bf16 v[4:7], v[8:11], v[230:233], v[124:127]
	v_mfma_f32_16x16x32_bf16 v[116:119], v[12:15], v[238:241], v[4:7]
	v_mfma_f32_16x16x32_bf16 v[4:7], v[16:19], v[196:199], v[120:123]
	v_mfma_f32_16x16x32_bf16 v[100:103], v[24:27], v[226:229], v[4:7]
	v_mfma_f32_16x16x32_bf16 v[4:7], v[16:19], v[230:233], v[132:135]
	v_mfma_f32_16x16x32_bf16 v[108:111], v[24:27], v[238:241], v[4:7]
	v_mfma_f32_16x16x32_bf16 v[4:7], v[28:31], v[196:199], v[112:115]
	v_mfma_f32_16x16x32_bf16 v[92:95], v[32:35], v[226:229], v[4:7]
	v_mfma_f32_16x16x32_bf16 v[4:7], v[28:31], v[230:233], v[206:209]
	v_mfma_f32_16x16x32_bf16 v[96:99], v[32:35], v[238:241], v[4:7]
	v_mfma_f32_16x16x32_bf16 v[4:7], v[242:245], v[196:199], v[210:213]
	v_mfma_f32_16x16x32_bf16 v[84:87], v[246:249], v[226:229], v[4:7]
	v_mfma_f32_16x16x32_bf16 v[4:7], v[242:245], v[230:233], v[214:217]
	v_mfma_f32_16x16x32_bf16 v[88:91], v[246:249], v[238:241], v[4:7]
	s_barrier
	ds_read_b128 v[132:135], v158
	ds_read_b128 v[204:207], v158 offset:1024
	ds_read_b128 v[208:211], v158 offset:2048
	ds_read_b128 v[158:161], v158 offset:3072
	s_waitcnt vmcnt(0)
	s_barrier
	s_waitcnt lgkmcnt(0)
	v_mfma_f32_16x16x32_bf16 v[4:7], v[8:11], v[132:135], v[218:221]
	v_mfma_f32_16x16x32_bf16 v[8:11], v[8:11], v[208:211], v[172:175]
	v_mfma_f32_16x16x32_bf16 v[4:7], v[12:15], v[204:207], v[4:7]
	v_mfma_f32_16x16x32_bf16 v[20:23], v[12:15], v[158:161], v[8:11]
	v_mfma_f32_16x16x32_bf16 v[8:11], v[16:19], v[132:135], v[176:179]
	v_mfma_f32_16x16x32_bf16 v[12:15], v[16:19], v[208:211], v[180:183]
	v_mfma_f32_16x16x32_bf16 v[8:11], v[24:27], v[204:207], v[8:11]
	v_mfma_f32_16x16x32_bf16 v[24:27], v[24:27], v[158:161], v[12:15]
	v_mfma_f32_16x16x32_bf16 v[12:15], v[28:31], v[132:135], v[80:83]
	v_mfma_f32_16x16x32_bf16 v[16:19], v[28:31], v[208:211], v[76:79]
	v_mfma_f32_16x16x32_bf16 v[12:15], v[32:35], v[204:207], v[12:15]
	v_mfma_f32_16x16x32_bf16 v[28:31], v[32:35], v[158:161], v[16:19]
	v_mfma_f32_16x16x32_bf16 v[16:19], v[242:245], v[132:135], v[72:75]
	v_mfma_f32_16x16x32_bf16 v[32:35], v[242:245], v[208:211], v[68:71]
	v_mfma_f32_16x16x32_bf16 v[16:19], v[246:249], v[204:207], v[16:19]
	v_mfma_f32_16x16x32_bf16 v[32:35], v[246:249], v[158:161], v[32:35]
	s_barrier
	ds_read_b128 v[170:173], v156 offset:49152
	ds_read_b128 v[174:177], v156 offset:50176
	ds_read_b128 v[178:181], v155 offset:49152
	ds_read_b128 v[212:215], v155 offset:50176
	ds_read_b128 v[216:219], v154 offset:49152
	ds_read_b128 v[154:157], v154 offset:50176
	ds_read_b128 v[220:223], v153 offset:49152
	ds_read_b128 v[150:153], v153 offset:50176
	s_waitcnt lgkmcnt(0)
	v_mfma_f32_16x16x32_bf16 v[64:67], v[170:173], v[196:199], v[64:67]
	v_mfma_f32_16x16x32_bf16 v[60:63], v[170:173], v[230:233], v[60:63]
	v_mfma_f32_16x16x32_bf16 v[56:59], v[178:181], v[196:199], v[56:59]
	v_mfma_f32_16x16x32_bf16 v[52:55], v[178:181], v[230:233], v[52:55]
	v_mfma_f32_16x16x32_bf16 v[48:51], v[216:219], v[196:199], v[48:51]
	v_mfma_f32_16x16x32_bf16 v[44:47], v[216:219], v[230:233], v[44:47]
	v_mfma_f32_16x16x32_bf16 v[40:43], v[220:223], v[196:199], v[40:43]
	v_mfma_f32_16x16x32_bf16 v[36:39], v[220:223], v[230:233], v[36:39]
	v_mfma_f32_16x16x32_bf16 v[128:131], v[174:177], v[226:229], v[64:67]
	v_mfma_f32_16x16x32_bf16 v[124:127], v[174:177], v[238:241], v[60:63]
	v_mfma_f32_16x16x32_bf16 v[120:123], v[212:215], v[226:229], v[56:59]
	v_mfma_f32_16x16x32_bf16 v[112:115], v[212:215], v[238:241], v[52:55]
	v_mfma_f32_16x16x32_bf16 v[80:83], v[154:157], v[226:229], v[48:51]
	v_mfma_f32_16x16x32_bf16 v[76:79], v[154:157], v[238:241], v[44:47]
	v_mfma_f32_16x16x32_bf16 v[72:75], v[150:153], v[226:229], v[40:43]
	v_mfma_f32_16x16x32_bf16 v[68:71], v[150:153], v[238:241], v[36:39]
	v_mfma_f32_16x16x32_bf16 v[40:43], v[170:173], v[208:211], v[140:143]
	v_mfma_f32_16x16x32_bf16 v[44:47], v[178:181], v[208:211], v[166:169]
	v_mfma_f32_16x16x32_bf16 v[48:51], v[216:219], v[208:211], v[184:187]
	v_mfma_f32_16x16x32_bf16 v[36:39], v[170:173], v[132:135], v[136:139]
	v_mfma_f32_16x16x32_bf16 v[52:55], v[174:177], v[158:161], v[40:43]
	v_mfma_f32_16x16x32_bf16 v[40:43], v[178:181], v[132:135], v[162:165]
	v_mfma_f32_16x16x32_bf16 v[56:59], v[212:215], v[158:161], v[44:47]
	v_mfma_f32_16x16x32_bf16 v[44:47], v[216:219], v[132:135], v[200:203]
	v_mfma_f32_16x16x32_bf16 v[60:63], v[154:157], v[158:161], v[48:51]
	v_mfma_f32_16x16x32_bf16 v[48:51], v[220:223], v[132:135], v[188:191]
	v_mfma_f32_16x16x32_bf16 v[64:67], v[220:223], v[208:211], v[192:195]
	v_mfma_f32_16x16x32_bf16 v[36:39], v[174:177], v[204:207], v[36:39]
	v_mfma_f32_16x16x32_bf16 v[40:43], v[212:215], v[204:207], v[40:43]
	v_mfma_f32_16x16x32_bf16 v[44:47], v[154:157], v[204:207], v[44:47]
	v_mfma_f32_16x16x32_bf16 v[48:51], v[150:153], v[204:207], v[48:51]
	v_mfma_f32_16x16x32_bf16 v[64:67], v[150:153], v[158:161], v[64:67]
	s_movk_i32 s2, 0x100
	v_cmp_gt_u32_e32 vcc, s2, v3
	s_barrier
	s_and_saveexec_b64 s[2:3], vcc
	s_cbranch_execz .LBB0_1155
	s_barrier

; #define LDA8(dst, b, h) _Pragma("unroll") for (int m = 0; m < 4; ++m) _Pragma("unroll") for (int k = 0; k < 2; ++k) \
;     dst[m][k] = *(const bf16x8*)((const char*)SA8(b, h) + lds_byte8(wr * 64 + m * 16 + fr, k * 32 + fq * 8))
; #define LDB8(dst, b, h) _Pragma("unroll") for (int n = 0; n < 2; ++n) _Pragma("unroll") for (int k = 0; k < 2; ++k) \
;     dst[n][k] = *(const bf16x8*)((const char*)SB8(b, h) + lds_byte8(wc * 32 + n * 16 + fr, k * 32 + fq * 8))
; #define WAIT_V8(n) asm volatile("s_waitcnt vmcnt(" #n ")" ::: "memory")
; #define WAIT_L8(n) asm volatile("s_waitcnt lgkmcnt(" #n ")" ::: "memory")
; #define BAR8 __builtin_amdgcn_s_barrier()
;     ...
;   { LDB8(B0, 0, 0); LDA8(At, 0, 0); STAGE8(SA8(1, 1), A, lda, brow + 128, nt - 1);
;     BAR8; WAIT_L8(0); MMA8(0, 0, At, B0); BAR8;
;     LDB8(B1, 0, 1); BAR8; WAIT_L8(0); MMA8(0, 1, At, B1); BAR8;
;     LDA8(At, 0, 1); WAIT_V8(4); BAR8; WAIT_L8(0); MMA8(1, 0, At, B0); MMA8(1, 1, At, B1); BAR8; }
.Lpk_exit_6:
	s_add_u32 s8, s8, 0x40780
	s_addc_u32 s9, s9, 0
	v_lshl_add_u64 v[132:133], s[8:9], 0, v[132:133]
	v_lshl_add_u64 v[0:1], v[0:1], 1, v[132:133]
	s_or_b32 m0, s100, 0xc000
	ds_read_b128 v[138:141], v171
	ds_read_b128 v[142:145], v171 offset:1024
	ds_read_b128 v[150:153], v171 offset:2048
	ds_read_b128 v[154:157], v171 offset:3072
	ds_read_b128 v[164:167], v161
	ds_read_b128 v[174:177], v161 offset:1024
	ds_read_b128 v[178:181], v160
	ds_read_b128 v[182:185], v160 offset:1024
	ds_read_b128 v[186:189], v159
	ds_read_b128 v[190:193], v159 offset:1024
	ds_read_b128 v[194:197], v158
	ds_read_b128 v[198:201], v158 offset:1024
	global_load_lds_dwordx4 v[0:1], off
	v_lshl_add_u64 v[0:1], s[8:9], 0, v[136:137]
	s_or_b32 m0, s100, 0xe000
	v_lshl_add_u64 v[0:1], v[134:135], 1, v[0:1]
	global_load_lds_dwordx4 v[0:1], off
	s_barrier
	s_waitcnt lgkmcnt(0)
	v_mfma_f32_16x16x32_f16 v[128:131], v[164:167], v[138:141], v[128:131]
	v_mfma_f32_16x16x32_f16 v[124:127], v[164:167], v[150:153], v[124:127]
	v_mfma_f32_16x16x32_f16 v[120:123], v[178:181], v[138:141], v[120:123]
	v_mfma_f32_16x16x32_f16 v[116:119], v[178:181], v[150:153], v[116:119]
	v_mfma_f32_16x16x32_f16 v[104:107], v[194:197], v[138:141], v[104:107]
	v_mfma_f32_16x16x32_f16 v[100:103], v[194:197], v[150:153], v[100:103]
	v_mfma_f32_16x16x32_f16 v[128:131], v[174:177], v[142:145], v[128:131]
	v_mfma_f32_16x16x32_f16 v[124:127], v[174:177], v[154:157], v[124:127]
	v_mfma_f32_16x16x32_f16 v[120:123], v[182:185], v[142:145], v[120:123]
	v_mfma_f32_16x16x32_f16 v[116:119], v[182:185], v[154:157], v[116:119]
	v_mfma_f32_16x16x32_f16 v[112:115], v[186:189], v[138:141], v[112:115]
	v_mfma_f32_16x16x32_f16 v[108:111], v[186:189], v[150:153], v[108:111]
	v_mfma_f32_16x16x32_f16 v[104:107], v[198:201], v[142:145], v[104:107]
	v_mfma_f32_16x16x32_f16 v[100:103], v[198:201], v[154:157], v[100:103]
	v_mfma_f32_16x16x32_f16 v[132:135], v[190:193], v[142:145], v[112:115]
	v_mfma_f32_16x16x32_f16 v[170:173], v[190:193], v[154:157], v[108:111]
	s_barrier
	s_nop 1
	ds_read_b128 v[108:111], v169
	ds_read_b128 v[112:115], v169 offset:1024
	ds_read_b128 v[202:205], v169 offset:2048
	ds_read_b128 v[206:209], v169 offset:3072
	s_barrier
	s_waitcnt lgkmcnt(0)
	v_mfma_f32_16x16x32_f16 v[88:91], v[178:181], v[108:111], v[88:91]
	v_mfma_f32_16x16x32_f16 v[84:87], v[178:181], v[202:205], v[84:87]
	v_mfma_f32_16x16x32_f16 v[72:75], v[194:197], v[108:111], v[72:75]
	v_mfma_f32_16x16x32_f16 v[68:71], v[194:197], v[202:205], v[68:71]
	v_mfma_f32_16x16x32_f16 v[96:99], v[164:167], v[108:111], v[96:99]
	v_mfma_f32_16x16x32_f16 v[92:95], v[164:167], v[202:205], v[92:95]
	v_mfma_f32_16x16x32_f16 v[88:91], v[182:185], v[112:115], v[88:91]
	v_mfma_f32_16x16x32_f16 v[84:87], v[182:185], v[206:209], v[84:87]
	v_mfma_f32_16x16x32_f16 v[80:83], v[186:189], v[108:111], v[80:83]
	v_mfma_f32_16x16x32_f16 v[76:79], v[186:189], v[202:205], v[76:79]
	v_mfma_f32_16x16x32_f16 v[72:75], v[198:201], v[112:115], v[72:75]
	v_mfma_f32_16x16x32_f16 v[68:71], v[198:201], v[206:209], v[68:71]
	v_mfma_f32_16x16x32_f16 v[210:213], v[174:177], v[112:115], v[96:99]
	v_mfma_f32_16x16x32_f16 v[164:167], v[174:177], v[206:209], v[92:95]
	v_mfma_f32_16x16x32_f16 v[174:177], v[190:193], v[112:115], v[80:83]
	v_mfma_f32_16x16x32_f16 v[178:181], v[190:193], v[206:209], v[76:79]
	s_barrier
	s_nop 0
	ds_read_b128 v[76:79], v161 offset:16384
	ds_read_b128 v[80:83], v161 offset:17408
	ds_read_b128 v[92:95], v160 offset:16384
	ds_read_b128 v[96:99], v160 offset:17408
	ds_read_b128 v[182:185], v159 offset:16384
	ds_read_b128 v[186:189], v159 offset:17408
	ds_read_b128 v[190:193], v158 offset:16384
	ds_read_b128 v[194:197], v158 offset:17408
	s_waitcnt vmcnt(4)
	s_barrier
	s_waitcnt lgkmcnt(0)
	v_mfma_f32_16x16x32_f16 v[64:67], v[76:79], v[138:141], v[64:67]
	v_mfma_f32_16x16x32_f16 v[60:63], v[76:79], v[150:153], v[60:63]
	v_mfma_f32_16x16x32_f16 v[56:59], v[92:95], v[138:141], v[56:59]
	v_mfma_f32_16x16x32_f16 v[52:55], v[92:95], v[150:153], v[52:55]
	v_mfma_f32_16x16x32_f16 v[40:43], v[190:193], v[138:141], v[40:43]
	v_mfma_f32_16x16x32_f16 v[36:39], v[190:193], v[150:153], v[36:39]
	v_mfma_f32_16x16x32_f16 v[64:67], v[80:83], v[142:145], v[64:67]
	v_mfma_f32_16x16x32_f16 v[60:63], v[80:83], v[154:157], v[60:63]
	v_mfma_f32_16x16x32_f16 v[56:59], v[96:99], v[142:145], v[56:59]
	v_mfma_f32_16x16x32_f16 v[52:55], v[96:99], v[154:157], v[52:55]
	v_mfma_f32_16x16x32_f16 v[48:51], v[182:185], v[138:141], v[48:51]
	v_mfma_f32_16x16x32_f16 v[44:47], v[182:185], v[150:153], v[44:47]
	v_mfma_f32_16x16x32_f16 v[40:43], v[194:197], v[142:145], v[40:43]
	v_mfma_f32_16x16x32_f16 v[36:39], v[194:197], v[154:157], v[36:39]
	v_mfma_f32_16x16x32_f16 v[198:201], v[186:189], v[142:145], v[48:51]
	v_mfma_f32_16x16x32_f16 v[214:217], v[186:189], v[154:157], v[44:47]
	v_mfma_f32_16x16x32_f16 v[24:27], v[92:95], v[108:111], v[24:27]
	v_mfma_f32_16x16x32_f16 v[20:23], v[92:95], v[202:205], v[20:23]
	v_mfma_f32_16x16x32_f16 v[8:11], v[190:193], v[108:111], v[8:11]
	v_mfma_f32_16x16x32_f16 v[4:7], v[190:193], v[202:205], v[4:7]
	v_mfma_f32_16x16x32_f16 v[32:35], v[76:79], v[108:111], v[32:35]
	v_mfma_f32_16x16x32_f16 v[28:31], v[76:79], v[202:205], v[28:31]
	v_mfma_f32_16x16x32_f16 v[24:27], v[96:99], v[112:115], v[24:27]
	v_mfma_f32_16x16x32_f16 v[20:23], v[96:99], v[206:209], v[20:23]
	v_mfma_f32_16x16x32_f16 v[16:19], v[182:185], v[108:111], v[16:19]
	v_mfma_f32_16x16x32_f16 v[12:15], v[182:185], v[202:205], v[12:15]
	v_mfma_f32_16x16x32_f16 v[8:11], v[194:197], v[112:115], v[8:11]
	v_mfma_f32_16x16x32_f16 v[4:7], v[194:197], v[206:209], v[4:7]
	v_mfma_f32_16x16x32_f16 v[136:139], v[80:83], v[112:115], v[32:35]
	v_mfma_f32_16x16x32_f16 v[140:143], v[80:83], v[206:209], v[28:31]
	v_mfma_f32_16x16x32_f16 v[150:153], v[186:189], v[112:115], v[16:19]
	v_mfma_f32_16x16x32_f16 v[154:157], v[186:189], v[206:209], v[12:15]
	s_barrier
; #define LDA8(dst, b, h) _Pragma("unroll") for (int m = 0; m < 4; ++m) _Pragma("unroll") for (int k = 0; k < 2; ++k) \
;     dst[m][k] = *(const bf16x8*)((const char*)SA8(b, h) + lds_byte8(wr * 64 + m * 16 + fr, k * 32 + fq * 8))
; #define LDB8(dst, b, h) _Pragma("unroll") for (int n = 0; n < 2; ++n) _Pragma("unroll") for (int k = 0; k < 2; ++k) \
;     dst[n][k] = *(const bf16x8*)((const char*)SB8(b, h) + lds_byte8(wc * 32 + n * 16 + fr, k * 32 + fq * 8))
; #define WAIT_V8(n) asm volatile("s_waitcnt vmcnt(" #n ")" ::: "memory")
; #define WAIT_L8(n) asm volatile("s_waitcnt lgkmcnt(" #n ")" ::: "memory")
; #define BAR8 __builtin_amdgcn_s_barrier()
;     ...
;   { LDB8(B0, 1, 0); LDA8(At, 1, 0); WAIT_V8(2); BAR8; WAIT_L8(0); MMA8(0, 0, At, B0); BAR8;
;     LDB8(B1, 1, 1); WAIT_V8(0); BAR8; WAIT_L8(0); MMA8(0, 1, At, B1); BAR8;
;     LDA8(At, 1, 1); BAR8; WAIT_L8(0); MMA8(1, 0, At, B0); MMA8(1, 1, At, B1); BAR8; }
;   if (wr == 0) BAR8;
;   __syncthreads();
	s_nop 0
	ds_read_b128 v[12:15], v163
	ds_read_b128 v[16:19], v163 offset:1024
	ds_read_b128 v[182:185], v163 offset:2048
	ds_read_b128 v[186:189], v163 offset:3072
	ds_read_b128 v[28:31], v161 offset:32768
	ds_read_b128 v[32:35], v161 offset:33792
	ds_read_b128 v[44:47], v160 offset:32768
	ds_read_b128 v[48:51], v160 offset:33792
	ds_read_b128 v[190:193], v159 offset:32768
	ds_read_b128 v[194:197], v159 offset:33792
	ds_read_b128 v[202:205], v158 offset:32768
	ds_read_b128 v[206:209], v158 offset:33792
	s_waitcnt vmcnt(2)
	s_barrier
	s_waitcnt lgkmcnt(0)
	v_mfma_f32_16x16x32_f16 v[76:79], v[28:31], v[12:15], v[128:131]
	v_mfma_f32_16x16x32_f16 v[128:131], v[32:35], v[16:19], v[76:79]
	v_mfma_f32_16x16x32_f16 v[76:79], v[28:31], v[182:185], v[124:127]
	v_mfma_f32_16x16x32_f16 v[124:127], v[32:35], v[186:189], v[76:79]
	v_mfma_f32_16x16x32_f16 v[76:79], v[44:47], v[12:15], v[120:123]
	v_mfma_f32_16x16x32_f16 v[112:115], v[48:51], v[16:19], v[76:79]
	v_mfma_f32_16x16x32_f16 v[76:79], v[44:47], v[182:185], v[116:119]
	v_mfma_f32_16x16x32_f16 v[108:111], v[48:51], v[186:189], v[76:79]
	v_mfma_f32_16x16x32_f16 v[76:79], v[190:193], v[12:15], v[132:135]
	v_mfma_f32_16x16x32_f16 v[96:99], v[194:197], v[16:19], v[76:79]
	v_mfma_f32_16x16x32_f16 v[76:79], v[190:193], v[182:185], v[170:173]
	v_mfma_f32_16x16x32_f16 v[92:95], v[194:197], v[186:189], v[76:79]
	v_mfma_f32_16x16x32_f16 v[76:79], v[202:205], v[12:15], v[104:107]
	v_mfma_f32_16x16x32_f16 v[80:83], v[206:209], v[16:19], v[76:79]
	v_mfma_f32_16x16x32_f16 v[76:79], v[202:205], v[182:185], v[100:103]
	v_mfma_f32_16x16x32_f16 v[76:79], v[206:209], v[186:189], v[76:79]
	s_barrier
	ds_read_b128 v[132:135], v162
	ds_read_b128 v[168:171], v162 offset:1024
	ds_read_b128 v[218:221], v162 offset:2048
	ds_read_b128 v[226:229], v162 offset:3072
	s_waitcnt vmcnt(0)
	s_barrier
	s_waitcnt lgkmcnt(0)
	v_mfma_f32_16x16x32_f16 v[100:103], v[28:31], v[132:135], v[210:213]
	v_mfma_f32_16x16x32_f16 v[28:31], v[28:31], v[218:221], v[164:167]
	v_mfma_f32_16x16x32_f16 v[116:119], v[32:35], v[226:229], v[28:31]
	v_mfma_f32_16x16x32_f16 v[28:31], v[44:47], v[132:135], v[88:91]
	v_mfma_f32_16x16x32_f16 v[104:107], v[48:51], v[168:171], v[28:31]
	v_mfma_f32_16x16x32_f16 v[28:31], v[44:47], v[218:221], v[84:87]
	v_mfma_f32_16x16x32_f16 v[120:123], v[32:35], v[168:171], v[100:103]
	v_mfma_f32_16x16x32_f16 v[100:103], v[48:51], v[226:229], v[28:31]
	v_mfma_f32_16x16x32_f16 v[28:31], v[190:193], v[132:135], v[174:177]
	v_mfma_f32_16x16x32_f16 v[88:91], v[194:197], v[168:171], v[28:31]
	v_mfma_f32_16x16x32_f16 v[28:31], v[190:193], v[218:221], v[178:181]
	v_mfma_f32_16x16x32_f16 v[84:87], v[194:197], v[226:229], v[28:31]
	v_mfma_f32_16x16x32_f16 v[28:31], v[202:205], v[132:135], v[72:75]
	v_mfma_f32_16x16x32_f16 v[72:75], v[206:209], v[168:171], v[28:31]
	v_mfma_f32_16x16x32_f16 v[28:31], v[202:205], v[218:221], v[68:71]
	v_mfma_f32_16x16x32_f16 v[68:71], v[206:209], v[226:229], v[28:31]
	s_barrier
	ds_read_b128 v[162:165], v161 offset:49152
	ds_read_b128 v[172:175], v161 offset:50176
	ds_read_b128 v[176:179], v160 offset:49152
	ds_read_b128 v[190:193], v160 offset:50176
	ds_read_b128 v[194:197], v159 offset:49152
	ds_read_b128 v[202:205], v159 offset:50176
	ds_read_b128 v[206:209], v158 offset:49152
	ds_read_b128 v[158:161], v158 offset:50176
	s_waitcnt lgkmcnt(0)
	v_mfma_f32_16x16x32_f16 v[28:31], v[162:165], v[12:15], v[64:67]
	v_mfma_f32_16x16x32_f16 v[64:67], v[172:175], v[16:19], v[28:31]
	v_mfma_f32_16x16x32_f16 v[28:31], v[162:165], v[182:185], v[60:63]
	v_mfma_f32_16x16x32_f16 v[60:63], v[172:175], v[186:189], v[28:31]
	v_mfma_f32_16x16x32_f16 v[28:31], v[176:179], v[12:15], v[56:59]
	v_mfma_f32_16x16x32_f16 v[48:51], v[190:193], v[16:19], v[28:31]
	v_mfma_f32_16x16x32_f16 v[28:31], v[176:179], v[182:185], v[52:55]
	v_mfma_f32_16x16x32_f16 v[44:47], v[190:193], v[186:189], v[28:31]
	v_mfma_f32_16x16x32_f16 v[28:31], v[194:197], v[12:15], v[198:201]
	v_mfma_f32_16x16x32_f16 v[12:15], v[206:209], v[12:15], v[40:43]
	v_mfma_f32_16x16x32_f16 v[32:35], v[202:205], v[16:19], v[28:31]
	v_mfma_f32_16x16x32_f16 v[28:31], v[194:197], v[182:185], v[214:217]
	v_mfma_f32_16x16x32_f16 v[16:19], v[158:161], v[16:19], v[12:15]
	v_mfma_f32_16x16x32_f16 v[12:15], v[206:209], v[182:185], v[36:39]
	v_mfma_f32_16x16x32_f16 v[28:31], v[202:205], v[186:189], v[28:31]
	v_mfma_f32_16x16x32_f16 v[12:15], v[158:161], v[186:189], v[12:15]
	v_mfma_f32_16x16x32_f16 v[36:39], v[162:165], v[132:135], v[136:139]
	v_mfma_f32_16x16x32_f16 v[56:59], v[172:175], v[168:171], v[36:39]
	v_mfma_f32_16x16x32_f16 v[36:39], v[162:165], v[218:221], v[140:143]
	v_mfma_f32_16x16x32_f16 v[20:23], v[176:179], v[218:221], v[20:23]
	v_mfma_f32_16x16x32_f16 v[52:55], v[172:175], v[226:229], v[36:39]
	v_mfma_f32_16x16x32_f16 v[24:27], v[176:179], v[132:135], v[24:27]
	v_mfma_f32_16x16x32_f16 v[36:39], v[190:193], v[226:229], v[20:23]
	v_mfma_f32_16x16x32_f16 v[20:23], v[194:197], v[132:135], v[150:153]
	v_mfma_f32_16x16x32_f16 v[40:43], v[190:193], v[168:171], v[24:27]
	v_mfma_f32_16x16x32_f16 v[24:27], v[202:205], v[168:171], v[20:23]
	v_mfma_f32_16x16x32_f16 v[20:23], v[194:197], v[218:221], v[154:157]
	v_mfma_f32_16x16x32_f16 v[8:11], v[206:209], v[132:135], v[8:11]
	v_mfma_f32_16x16x32_f16 v[4:7], v[206:209], v[218:221], v[4:7]
	v_mfma_f32_16x16x32_f16 v[20:23], v[202:205], v[226:229], v[20:23]
	v_mfma_f32_16x16x32_f16 v[8:11], v[158:161], v[168:171], v[8:11]
	v_mfma_f32_16x16x32_f16 v[4:7], v[158:161], v[226:229], v[4:7]
	s_movk_i32 s1, 0x100
	v_cmp_gt_u32_e32 vcc, s1, v3
	s_barrier
	s_and_saveexec_b64 s[8:9], vcc
	s_cbranch_execz .LBB0_1262
	s_barrier

; #define LDA8(dst, b, h) _Pragma("unroll") for (int m = 0; m < 4; ++m) _Pragma("unroll") for (int k = 0; k < 2; ++k) \
;     dst[m][k] = *(const bf16x8*)((const char*)SA8(b, h) + lds_byte8(wr * 64 + m * 16 + fr, k * 32 + fq * 8))
; #define LDB8(dst, b, h) _Pragma("unroll") for (int n = 0; n < 2; ++n) _Pragma("unroll") for (int k = 0; k < 2; ++k) \
;     dst[n][k] = *(const bf16x8*)((const char*)SB8(b, h) + lds_byte8(wc * 32 + n * 16 + fr, k * 32 + fq * 8))
; #define WAIT_V8(n) asm volatile("s_waitcnt vmcnt(" #n ")" ::: "memory")
; #define WAIT_L8(n) asm volatile("s_waitcnt lgkmcnt(" #n ")" ::: "memory")
; #define BAR8 __builtin_amdgcn_s_barrier()
;     ...
;   { LDB8(B0, 0, 0); LDA8(At, 0, 0); STAGE8(SA8(1, 1), A, lda, brow + 128, nt - 1);
;     BAR8; WAIT_L8(0); MMA8(0, 0, At, B0); BAR8;
;     LDB8(B1, 0, 1); BAR8; WAIT_L8(0); MMA8(0, 1, At, B1); BAR8;
;     LDA8(At, 0, 1); WAIT_V8(4); BAR8; WAIT_L8(0); MMA8(1, 0, At, B0); MMA8(1, 1, At, B1); BAR8; }
.Lpk_exit_7:
	s_add_i32 s27, s27, 0xb0000
	s_add_u32 s2, s2, s27
	s_addc_u32 s3, s3, 0
	s_add_u32 s2, s2, 0x2001580
	s_addc_u32 s3, s3, 0
	v_lshl_add_u64 v[132:133], v[132:133], 1, s[2:3]
	v_lshl_add_u64 v[0:1], v[0:1], 1, v[132:133]
	s_or_b32 m0, s100, 0xc000
	ds_read_b128 v[138:141], v171
	ds_read_b128 v[142:145], v171 offset:1024
	ds_read_b128 v[160:163], v171 offset:2048
	ds_read_b128 v[164:167], v171 offset:3072
	ds_read_b128 v[174:177], v156
	ds_read_b128 v[178:181], v156 offset:1024
	ds_read_b128 v[182:185], v155
	ds_read_b128 v[186:189], v155 offset:1024
	ds_read_b128 v[190:193], v154
	ds_read_b128 v[194:197], v154 offset:1024
	ds_read_b128 v[198:201], v153
	ds_read_b128 v[202:205], v153 offset:1024
	global_load_lds_dwordx4 v[0:1], off
	v_lshl_add_u64 v[0:1], v[136:137], 1, s[2:3]
	s_or_b32 m0, s100, 0xe000
	v_lshl_add_u64 v[0:1], v[134:135], 1, v[0:1]
	global_load_lds_dwordx4 v[0:1], off
	s_barrier
	s_waitcnt lgkmcnt(0)
	v_mfma_f32_16x16x32_bf16 v[128:131], v[174:177], v[138:141], v[128:131]
	v_mfma_f32_16x16x32_bf16 v[124:127], v[174:177], v[160:163], v[124:127]
	v_mfma_f32_16x16x32_bf16 v[120:123], v[182:185], v[138:141], v[120:123]
	v_mfma_f32_16x16x32_bf16 v[112:115], v[190:193], v[138:141], v[112:115]
	v_mfma_f32_16x16x32_bf16 v[128:131], v[178:181], v[142:145], v[128:131]
	v_mfma_f32_16x16x32_bf16 v[124:127], v[178:181], v[164:167], v[124:127]
	v_mfma_f32_16x16x32_bf16 v[120:123], v[186:189], v[142:145], v[120:123]
	v_mfma_f32_16x16x32_bf16 v[116:119], v[182:185], v[160:163], v[116:119]
	v_mfma_f32_16x16x32_bf16 v[112:115], v[194:197], v[142:145], v[112:115]
	v_mfma_f32_16x16x32_bf16 v[108:111], v[190:193], v[160:163], v[108:111]
	v_mfma_f32_16x16x32_bf16 v[104:107], v[198:201], v[138:141], v[104:107]
	v_mfma_f32_16x16x32_bf16 v[100:103], v[198:201], v[160:163], v[100:103]
	v_mfma_f32_16x16x32_bf16 v[132:135], v[186:189], v[164:167], v[116:119]
	v_mfma_f32_16x16x32_bf16 v[170:173], v[194:197], v[164:167], v[108:111]
	v_mfma_f32_16x16x32_bf16 v[206:209], v[202:205], v[142:145], v[104:107]
	v_mfma_f32_16x16x32_bf16 v[210:213], v[202:205], v[164:167], v[100:103]
	s_barrier
	s_nop 1
	ds_read_b128 v[100:103], v169
	ds_read_b128 v[104:107], v169 offset:1024
	ds_read_b128 v[108:111], v169 offset:2048
	ds_read_b128 v[116:119], v169 offset:3072
	s_barrier
	s_waitcnt lgkmcnt(0)
	v_mfma_f32_16x16x32_bf16 v[80:83], v[190:193], v[100:103], v[80:83]
	v_mfma_f32_16x16x32_bf16 v[76:79], v[190:193], v[108:111], v[76:79]
	v_mfma_f32_16x16x32_bf16 v[72:75], v[198:201], v[100:103], v[72:75]
	v_mfma_f32_16x16x32_bf16 v[68:71], v[198:201], v[108:111], v[68:71]
	v_mfma_f32_16x16x32_bf16 v[96:99], v[174:177], v[100:103], v[96:99]
	v_mfma_f32_16x16x32_bf16 v[92:95], v[174:177], v[108:111], v[92:95]
	v_mfma_f32_16x16x32_bf16 v[88:91], v[182:185], v[100:103], v[88:91]
	v_mfma_f32_16x16x32_bf16 v[84:87], v[182:185], v[108:111], v[84:87]
	v_mfma_f32_16x16x32_bf16 v[80:83], v[194:197], v[104:107], v[80:83]
	v_mfma_f32_16x16x32_bf16 v[76:79], v[194:197], v[116:119], v[76:79]
	v_mfma_f32_16x16x32_bf16 v[72:75], v[202:205], v[104:107], v[72:75]
	v_mfma_f32_16x16x32_bf16 v[68:71], v[202:205], v[116:119], v[68:71]
	v_mfma_f32_16x16x32_bf16 v[214:217], v[178:181], v[104:107], v[96:99]
	v_mfma_f32_16x16x32_bf16 v[174:177], v[178:181], v[116:119], v[92:95]
	v_mfma_f32_16x16x32_bf16 v[178:181], v[186:189], v[104:107], v[88:91]
	v_mfma_f32_16x16x32_bf16 v[182:185], v[186:189], v[116:119], v[84:87]
	s_barrier
	s_nop 0
	ds_read_b128 v[84:87], v156 offset:16384
	ds_read_b128 v[88:91], v156 offset:17408
	ds_read_b128 v[92:95], v155 offset:16384
	ds_read_b128 v[96:99], v155 offset:17408
	ds_read_b128 v[186:189], v154 offset:16384
	ds_read_b128 v[190:193], v154 offset:17408
	ds_read_b128 v[194:197], v153 offset:16384
	ds_read_b128 v[198:201], v153 offset:17408
	s_waitcnt vmcnt(4)
	s_barrier
	s_waitcnt lgkmcnt(0)
	v_mfma_f32_16x16x32_bf16 v[64:67], v[84:87], v[138:141], v[64:67]
	v_mfma_f32_16x16x32_bf16 v[60:63], v[84:87], v[160:163], v[60:63]
	v_mfma_f32_16x16x32_bf16 v[56:59], v[92:95], v[138:141], v[56:59]
	v_mfma_f32_16x16x32_bf16 v[52:55], v[92:95], v[160:163], v[52:55]
	v_mfma_f32_16x16x32_bf16 v[48:51], v[186:189], v[138:141], v[48:51]
	v_mfma_f32_16x16x32_bf16 v[44:47], v[186:189], v[160:163], v[44:47]
	v_mfma_f32_16x16x32_bf16 v[40:43], v[194:197], v[138:141], v[40:43]
	v_mfma_f32_16x16x32_bf16 v[36:39], v[194:197], v[160:163], v[36:39]
	v_mfma_f32_16x16x32_bf16 v[64:67], v[88:91], v[142:145], v[64:67]
	v_mfma_f32_16x16x32_bf16 v[60:63], v[88:91], v[164:167], v[60:63]
	v_mfma_f32_16x16x32_bf16 v[56:59], v[96:99], v[142:145], v[56:59]
	v_mfma_f32_16x16x32_bf16 v[52:55], v[96:99], v[164:167], v[52:55]
	v_mfma_f32_16x16x32_bf16 v[48:51], v[190:193], v[142:145], v[48:51]
	v_mfma_f32_16x16x32_bf16 v[44:47], v[190:193], v[164:167], v[44:47]
	v_mfma_f32_16x16x32_bf16 v[40:43], v[198:201], v[142:145], v[40:43]
	v_mfma_f32_16x16x32_bf16 v[36:39], v[198:201], v[164:167], v[36:39]
	v_mfma_f32_16x16x32_bf16 v[32:35], v[84:87], v[100:103], v[32:35]
	v_mfma_f32_16x16x32_bf16 v[28:31], v[84:87], v[108:111], v[28:31]
	v_mfma_f32_16x16x32_bf16 v[24:27], v[92:95], v[100:103], v[24:27]
	v_mfma_f32_16x16x32_bf16 v[20:23], v[92:95], v[108:111], v[20:23]
	v_mfma_f32_16x16x32_bf16 v[16:19], v[186:189], v[100:103], v[16:19]
	v_mfma_f32_16x16x32_bf16 v[12:15], v[186:189], v[108:111], v[12:15]
	v_mfma_f32_16x16x32_bf16 v[8:11], v[194:197], v[100:103], v[8:11]
	v_mfma_f32_16x16x32_bf16 v[4:7], v[194:197], v[108:111], v[4:7]
	v_mfma_f32_16x16x32_bf16 v[136:139], v[88:91], v[104:107], v[32:35]
	v_mfma_f32_16x16x32_bf16 v[140:143], v[88:91], v[116:119], v[28:31]
	v_mfma_f32_16x16x32_bf16 v[160:163], v[96:99], v[104:107], v[24:27]
	v_mfma_f32_16x16x32_bf16 v[164:167], v[96:99], v[116:119], v[20:23]
	v_mfma_f32_16x16x32_bf16 v[202:205], v[190:193], v[104:107], v[16:19]
	v_mfma_f32_16x16x32_bf16 v[186:189], v[190:193], v[116:119], v[12:15]
	v_mfma_f32_16x16x32_bf16 v[190:193], v[198:201], v[104:107], v[8:11]
	v_mfma_f32_16x16x32_bf16 v[194:197], v[198:201], v[116:119], v[4:7]
	s_barrier
; #define LDA8(dst, b, h) _Pragma("unroll") for (int m = 0; m < 4; ++m) _Pragma("unroll") for (int k = 0; k < 2; ++k) \
;     dst[m][k] = *(const bf16x8*)((const char*)SA8(b, h) + lds_byte8(wr * 64 + m * 16 + fr, k * 32 + fq * 8))
; #define LDB8(dst, b, h) _Pragma("unroll") for (int n = 0; n < 2; ++n) _Pragma("unroll") for (int k = 0; k < 2; ++k) \
;     dst[n][k] = *(const bf16x8*)((const char*)SB8(b, h) + lds_byte8(wc * 32 + n * 16 + fr, k * 32 + fq * 8))
; #define WAIT_V8(n) asm volatile("s_waitcnt vmcnt(" #n ")" ::: "memory")
; #define WAIT_L8(n) asm volatile("s_waitcnt lgkmcnt(" #n ")" ::: "memory")
; #define BAR8 __builtin_amdgcn_s_barrier()
;     ...
;   { LDB8(B0, 1, 0); LDA8(At, 1, 0); WAIT_V8(2); BAR8; WAIT_L8(0); MMA8(0, 0, At, B0); BAR8;
;     LDB8(B1, 1, 1); WAIT_V8(0); BAR8; WAIT_L8(0); MMA8(0, 1, At, B1); BAR8;
;     LDA8(At, 1, 1); BAR8; WAIT_L8(0); MMA8(1, 0, At, B0); MMA8(1, 1, At, B1); BAR8; }
;   if (wr == 0) BAR8;
;   __syncthreads();
	ds_read_b128 v[198:201], v159
	ds_read_b128 v[218:221], v159 offset:1024
	ds_read_b128 v[226:229], v159 offset:2048
	ds_read_b128 v[230:233], v159 offset:3072
	ds_read_b128 v[8:11], v156 offset:32768
	ds_read_b128 v[12:15], v156 offset:33792
	ds_read_b128 v[16:19], v155 offset:32768
	ds_read_b128 v[24:27], v155 offset:33792
	ds_read_b128 v[28:31], v154 offset:32768
	ds_read_b128 v[32:35], v154 offset:33792
	ds_read_b128 v[238:241], v153 offset:32768
	ds_read_b128 v[242:245], v153 offset:33792
	s_waitcnt vmcnt(2)
	s_barrier
	s_waitcnt lgkmcnt(0)
	v_mfma_f32_16x16x32_bf16 v[4:7], v[8:11], v[198:201], v[128:131]
	v_mfma_f32_16x16x32_bf16 v[104:107], v[12:15], v[218:221], v[4:7]
	v_mfma_f32_16x16x32_bf16 v[4:7], v[8:11], v[226:229], v[124:127]
	v_mfma_f32_16x16x32_bf16 v[116:119], v[12:15], v[230:233], v[4:7]
	v_mfma_f32_16x16x32_bf16 v[4:7], v[16:19], v[198:201], v[120:123]
	v_mfma_f32_16x16x32_bf16 v[100:103], v[24:27], v[218:221], v[4:7]
	v_mfma_f32_16x16x32_bf16 v[4:7], v[16:19], v[226:229], v[132:135]
	v_mfma_f32_16x16x32_bf16 v[108:111], v[24:27], v[230:233], v[4:7]
	v_mfma_f32_16x16x32_bf16 v[4:7], v[28:31], v[198:201], v[112:115]
	v_mfma_f32_16x16x32_bf16 v[92:95], v[32:35], v[218:221], v[4:7]
	v_mfma_f32_16x16x32_bf16 v[4:7], v[28:31], v[226:229], v[170:173]
	v_mfma_f32_16x16x32_bf16 v[96:99], v[32:35], v[230:233], v[4:7]
	v_mfma_f32_16x16x32_bf16 v[4:7], v[238:241], v[198:201], v[206:209]
	v_mfma_f32_16x16x32_bf16 v[84:87], v[242:245], v[218:221], v[4:7]
	v_mfma_f32_16x16x32_bf16 v[4:7], v[238:241], v[226:229], v[210:213]
	v_mfma_f32_16x16x32_bf16 v[88:91], v[242:245], v[230:233], v[4:7]
	s_barrier
	ds_read_b128 v[132:135], v158
	ds_read_b128 v[168:171], v158 offset:1024
	ds_read_b128 v[206:209], v158 offset:2048
	ds_read_b128 v[210:213], v158 offset:3072
	s_waitcnt vmcnt(0)
	s_barrier
	s_waitcnt lgkmcnt(0)
	v_mfma_f32_16x16x32_bf16 v[4:7], v[8:11], v[132:135], v[214:217]
	v_mfma_f32_16x16x32_bf16 v[8:11], v[8:11], v[206:209], v[174:177]
	v_mfma_f32_16x16x32_bf16 v[4:7], v[12:15], v[168:171], v[4:7]
	v_mfma_f32_16x16x32_bf16 v[20:23], v[12:15], v[210:213], v[8:11]
	v_mfma_f32_16x16x32_bf16 v[8:11], v[16:19], v[132:135], v[178:181]
	v_mfma_f32_16x16x32_bf16 v[12:15], v[16:19], v[206:209], v[182:185]
	v_mfma_f32_16x16x32_bf16 v[8:11], v[24:27], v[168:171], v[8:11]
	v_mfma_f32_16x16x32_bf16 v[24:27], v[24:27], v[210:213], v[12:15]
	v_mfma_f32_16x16x32_bf16 v[12:15], v[28:31], v[132:135], v[80:83]
	v_mfma_f32_16x16x32_bf16 v[16:19], v[28:31], v[206:209], v[76:79]
	v_mfma_f32_16x16x32_bf16 v[12:15], v[32:35], v[168:171], v[12:15]
	v_mfma_f32_16x16x32_bf16 v[28:31], v[32:35], v[210:213], v[16:19]
	v_mfma_f32_16x16x32_bf16 v[16:19], v[238:241], v[132:135], v[72:75]
	v_mfma_f32_16x16x32_bf16 v[32:35], v[238:241], v[206:209], v[68:71]
	v_mfma_f32_16x16x32_bf16 v[16:19], v[242:245], v[168:171], v[16:19]
	v_mfma_f32_16x16x32_bf16 v[32:35], v[242:245], v[210:213], v[32:35]
	s_barrier
	ds_read_b128 v[172:175], v156 offset:49152
	ds_read_b128 v[156:159], v156 offset:50176
	ds_read_b128 v[176:179], v155 offset:49152
	ds_read_b128 v[180:183], v155 offset:50176
	ds_read_b128 v[214:217], v154 offset:49152
	ds_read_b128 v[238:241], v154 offset:50176
	ds_read_b128 v[242:245], v153 offset:49152
	ds_read_b128 v[150:153], v153 offset:50176
	s_waitcnt lgkmcnt(0)
	v_mfma_f32_16x16x32_bf16 v[64:67], v[172:175], v[198:201], v[64:67]
	v_mfma_f32_16x16x32_bf16 v[60:63], v[172:175], v[226:229], v[60:63]
	v_mfma_f32_16x16x32_bf16 v[56:59], v[176:179], v[198:201], v[56:59]
	v_mfma_f32_16x16x32_bf16 v[52:55], v[176:179], v[226:229], v[52:55]
	v_mfma_f32_16x16x32_bf16 v[48:51], v[214:217], v[198:201], v[48:51]
	v_mfma_f32_16x16x32_bf16 v[44:47], v[214:217], v[226:229], v[44:47]
	v_mfma_f32_16x16x32_bf16 v[40:43], v[242:245], v[198:201], v[40:43]
	v_mfma_f32_16x16x32_bf16 v[36:39], v[242:245], v[226:229], v[36:39]
	v_mfma_f32_16x16x32_bf16 v[128:131], v[156:159], v[218:221], v[64:67]
	v_mfma_f32_16x16x32_bf16 v[124:127], v[156:159], v[230:233], v[60:63]
	v_mfma_f32_16x16x32_bf16 v[120:123], v[180:183], v[218:221], v[56:59]
	v_mfma_f32_16x16x32_bf16 v[112:115], v[180:183], v[230:233], v[52:55]
	v_mfma_f32_16x16x32_bf16 v[80:83], v[238:241], v[218:221], v[48:51]
	v_mfma_f32_16x16x32_bf16 v[76:79], v[238:241], v[230:233], v[44:47]
	v_mfma_f32_16x16x32_bf16 v[72:75], v[150:153], v[218:221], v[40:43]
	v_mfma_f32_16x16x32_bf16 v[68:71], v[150:153], v[230:233], v[36:39]
	v_mfma_f32_16x16x32_bf16 v[40:43], v[172:175], v[206:209], v[140:143]
	v_mfma_f32_16x16x32_bf16 v[44:47], v[176:179], v[206:209], v[164:167]
	v_mfma_f32_16x16x32_bf16 v[48:51], v[214:217], v[206:209], v[186:189]
	v_mfma_f32_16x16x32_bf16 v[36:39], v[172:175], v[132:135], v[136:139]
	v_mfma_f32_16x16x32_bf16 v[52:55], v[156:159], v[210:213], v[40:43]
	v_mfma_f32_16x16x32_bf16 v[40:43], v[176:179], v[132:135], v[160:163]
	v_mfma_f32_16x16x32_bf16 v[56:59], v[180:183], v[210:213], v[44:47]
	v_mfma_f32_16x16x32_bf16 v[44:47], v[214:217], v[132:135], v[202:205]
	v_mfma_f32_16x16x32_bf16 v[60:63], v[238:241], v[210:213], v[48:51]
	v_mfma_f32_16x16x32_bf16 v[48:51], v[242:245], v[132:135], v[190:193]
	v_mfma_f32_16x16x32_bf16 v[64:67], v[242:245], v[206:209], v[194:197]
	v_mfma_f32_16x16x32_bf16 v[36:39], v[156:159], v[168:171], v[36:39]
	v_mfma_f32_16x16x32_bf16 v[40:43], v[180:183], v[168:171], v[40:43]
	v_mfma_f32_16x16x32_bf16 v[44:47], v[238:241], v[168:171], v[44:47]
	v_mfma_f32_16x16x32_bf16 v[48:51], v[150:153], v[168:171], v[48:51]
	v_mfma_f32_16x16x32_bf16 v[64:67], v[150:153], v[210:213], v[64:67]
	s_movk_i32 s2, 0x100
	v_cmp_gt_u32_e32 vcc, s2, v3
	s_barrier
	s_and_saveexec_b64 s[2:3], vcc
	s_cbranch_execz .LBB0_1328
	s_barrier
